# GEMM K-loops: s_barrier moved up to directly follow the last MFMA of each block (address/loop-control instructions now after the barrier)
# baseline (speedup 1.0000x reference)
.LBB0_173:
	s_add_u32 s64, s62, 0x100
	s_addc_u32 s65, s63, 0
	s_add_i32 s34, 0, 0x10000
	v_add_u32_e32 v108, s34, v196
	ds_read_b128 v[96:99], v108
	ds_read_b128 v[100:103], v108 offset:1024
	ds_read_b128 v[104:107], v108 offset:2048
	ds_read_b128 v[158:161], v108 offset:3072
	s_cmp_eq_u32 s83, 28
	s_cselect_b32 s69, s57, s65
	s_cselect_b32 s68, s71, s64
	s_cselect_b32 s67, s55, s82
	s_cselect_b32 s66, s80, s81
	v_lshl_add_u64 v[108:109], s[62:63], 0, v[154:155]
	s_add_i32 m0, s44, 0xc000
	ds_read_b128 v[162:165], v207
	ds_read_b128 v[166:169], v207 offset:1024
	ds_read_b128 v[170:173], v207 offset:2048
	ds_read_b128 v[180:183], v207 offset:3072
	ds_read_b128 v[184:187], v207 offset:4096
	ds_read_b128 v[188:191], v207 offset:5120
	ds_read_b128 v[192:195], v207 offset:6144
	ds_read_b128 v[198:201], v207 offset:7168
	global_load_lds_dwordx4 v[108:109], off
	v_lshl_add_u64 v[108:109], s[62:63], 0, v[156:157]
	s_add_i32 m0, s44, 0xe000
	s_nop 0
	global_load_lds_dwordx4 v[108:109], off
	s_waitcnt lgkmcnt(8)
	s_barrier
	s_waitcnt lgkmcnt(0)
	v_mfma_f32_16x16x32_bf16 v[138:141], v[96:99], v[162:165], v[138:141]
	v_mfma_f32_16x16x32_bf16 v[60:63], v[104:107], v[162:165], v[60:63]
	v_mfma_f32_16x16x32_bf16 v[134:137], v[96:99], v[170:173], v[134:137]
	v_mfma_f32_16x16x32_bf16 v[56:59], v[104:107], v[170:173], v[56:59]
	v_mfma_f32_16x16x32_bf16 v[130:133], v[96:99], v[184:187], v[130:133]
	v_mfma_f32_16x16x32_bf16 v[52:55], v[104:107], v[184:187], v[52:55]
	v_mfma_f32_16x16x32_bf16 v[126:129], v[96:99], v[192:195], v[126:129]
	v_mfma_f32_16x16x32_bf16 v[48:51], v[104:107], v[192:195], v[48:51]
	v_mfma_f32_16x16x32_bf16 v[138:141], v[100:103], v[166:169], v[138:141]
	v_mfma_f32_16x16x32_bf16 v[60:63], v[158:161], v[166:169], v[60:63]
	v_mfma_f32_16x16x32_bf16 v[134:137], v[100:103], v[180:183], v[134:137]
	v_mfma_f32_16x16x32_bf16 v[56:59], v[158:161], v[180:183], v[56:59]
	v_mfma_f32_16x16x32_bf16 v[130:133], v[100:103], v[188:191], v[130:133]
	v_mfma_f32_16x16x32_bf16 v[52:55], v[158:161], v[188:191], v[52:55]
	v_mfma_f32_16x16x32_bf16 v[126:129], v[100:103], v[198:201], v[126:129]
	v_mfma_f32_16x16x32_bf16 v[48:51], v[158:161], v[198:201], v[48:51]
	s_barrier
	s_add_i32 s35, 0, 0x14000
	s_add_i32 s34, s34, s39
	v_add_u32_e32 v108, s35, v196
	v_lshl_add_u64 v[174:175], s[66:67], 0, v[146:147]
	s_mov_b32 m0, s34
	ds_read_b128 v[208:211], v108
	ds_read_b128 v[212:215], v108 offset:1024
	ds_read_b128 v[216:219], v108 offset:2048
	ds_read_b128 v[220:223], v108 offset:3072
	global_load_lds_dwordx4 v[174:175], off
	v_lshl_add_u64 v[224:225], s[66:67], 0, v[142:143]
	s_add_i32 m0, s34, 0x2000
	s_nop 0
	global_load_lds_dwordx4 v[224:225], off
	s_barrier
	s_waitcnt lgkmcnt(0)
	v_mfma_f32_16x16x32_bf16 v[122:125], v[208:211], v[162:165], v[122:125]
	v_mfma_f32_16x16x32_bf16 v[44:47], v[216:219], v[162:165], v[44:47]
	v_mfma_f32_16x16x32_bf16 v[114:117], v[208:211], v[170:173], v[114:117]
	v_mfma_f32_16x16x32_bf16 v[36:39], v[216:219], v[170:173], v[36:39]
	v_mfma_f32_16x16x32_bf16 v[118:121], v[208:211], v[184:187], v[118:121]
	v_mfma_f32_16x16x32_bf16 v[40:43], v[216:219], v[184:187], v[40:43]
	v_mfma_f32_16x16x32_bf16 v[108:111], v[208:211], v[192:195], v[110:113]
	v_mfma_f32_16x16x32_bf16 v[32:35], v[216:219], v[192:195], v[32:35]
	v_mfma_f32_16x16x32_bf16 v[122:125], v[212:215], v[166:169], v[122:125]
	v_mfma_f32_16x16x32_bf16 v[44:47], v[220:223], v[166:169], v[44:47]
	v_mfma_f32_16x16x32_bf16 v[114:117], v[212:215], v[180:183], v[114:117]
	v_mfma_f32_16x16x32_bf16 v[36:39], v[220:223], v[180:183], v[36:39]
	v_mfma_f32_16x16x32_bf16 v[118:121], v[212:215], v[188:191], v[118:121]
	v_mfma_f32_16x16x32_bf16 v[40:43], v[220:223], v[188:191], v[40:43]
	v_mfma_f32_16x16x32_bf16 v[108:111], v[212:215], v[198:201], v[108:111]
	v_mfma_f32_16x16x32_bf16 v[32:35], v[220:223], v[198:201], v[32:35]
	s_barrier
	s_mov_b32 m0, s44
	v_lshl_add_u64 v[226:227], s[68:69], 0, v[148:149]
	ds_read_b128 v[162:165], v207 offset:16384
	ds_read_b128 v[166:169], v207 offset:17408
	ds_read_b128 v[170:173], v207 offset:18432
	ds_read_b128 v[180:183], v207 offset:19456
	ds_read_b128 v[184:187], v207 offset:20480
	ds_read_b128 v[188:191], v207 offset:21504
	ds_read_b128 v[192:195], v207 offset:22528
	ds_read_b128 v[198:201], v207 offset:23552
	global_load_lds_dwordx4 v[226:227], off
	v_lshl_add_u64 v[228:229], s[68:69], 0, v[144:145]
	s_mov_b32 m0, s72
	s_nop 0
	global_load_lds_dwordx4 v[228:229], off
	s_barrier
	s_waitcnt lgkmcnt(0)
	v_mfma_f32_16x16x32_bf16 v[92:95], v[96:99], v[162:165], v[92:95]
	v_mfma_f32_16x16x32_bf16 v[28:31], v[104:107], v[162:165], v[28:31]
	v_mfma_f32_16x16x32_bf16 v[88:91], v[96:99], v[170:173], v[88:91]
	v_mfma_f32_16x16x32_bf16 v[24:27], v[104:107], v[170:173], v[24:27]
	v_mfma_f32_16x16x32_bf16 v[84:87], v[96:99], v[184:187], v[84:87]
	v_mfma_f32_16x16x32_bf16 v[20:23], v[104:107], v[184:187], v[20:23]
	v_mfma_f32_16x16x32_bf16 v[80:83], v[96:99], v[192:195], v[80:83]
	v_mfma_f32_16x16x32_bf16 v[16:19], v[104:107], v[192:195], v[16:19]
	v_mfma_f32_16x16x32_bf16 v[92:95], v[100:103], v[166:169], v[92:95]
	v_mfma_f32_16x16x32_bf16 v[28:31], v[158:161], v[166:169], v[28:31]
	v_mfma_f32_16x16x32_bf16 v[88:91], v[100:103], v[180:183], v[88:91]
	v_mfma_f32_16x16x32_bf16 v[24:27], v[158:161], v[180:183], v[24:27]
	v_mfma_f32_16x16x32_bf16 v[84:87], v[100:103], v[188:191], v[84:87]
	v_mfma_f32_16x16x32_bf16 v[20:23], v[158:161], v[188:191], v[20:23]
	v_mfma_f32_16x16x32_bf16 v[80:83], v[100:103], v[198:201], v[80:83]
	v_mfma_f32_16x16x32_bf16 v[16:19], v[158:161], v[198:201], v[16:19]
	s_barrier
	s_add_u32 s62, s66, 0x80000
	s_addc_u32 s63, s67, 0
	s_add_i32 s34, s35, s39
	v_lshl_add_u64 v[96:97], s[62:63], 0, v[146:147]
	s_mov_b32 m0, s34
	s_nop 0
	global_load_lds_dwordx4 v[96:97], off
	v_lshl_add_u64 v[96:97], s[62:63], 0, v[142:143]
	s_add_i32 m0, s34, 0x2000
	s_nop 0
	global_load_lds_dwordx4 v[96:97], off
	s_waitcnt vmcnt(6)
	s_barrier
	v_mfma_f32_16x16x32_bf16 v[76:79], v[208:211], v[162:165], v[76:79]
	v_mfma_f32_16x16x32_bf16 v[12:15], v[216:219], v[162:165], v[12:15]
	v_mfma_f32_16x16x32_bf16 v[68:71], v[208:211], v[170:173], v[68:71]
	v_mfma_f32_16x16x32_bf16 v[4:7], v[216:219], v[170:173], v[4:7]
	v_mfma_f32_16x16x32_bf16 v[72:75], v[208:211], v[184:187], v[72:75]
	v_mfma_f32_16x16x32_bf16 v[8:11], v[216:219], v[184:187], v[8:11]
	v_mfma_f32_16x16x32_bf16 v[64:67], v[208:211], v[192:195], v[64:67]
	v_mfma_f32_16x16x32_bf16 v[0:3], v[216:219], v[192:195], v[0:3]
	v_mfma_f32_16x16x32_bf16 v[76:79], v[212:215], v[166:169], v[76:79]
	v_mfma_f32_16x16x32_bf16 v[12:15], v[220:223], v[166:169], v[12:15]
	v_mfma_f32_16x16x32_bf16 v[68:71], v[212:215], v[180:183], v[68:71]
	v_mfma_f32_16x16x32_bf16 v[4:7], v[220:223], v[180:183], v[4:7]
	v_mfma_f32_16x16x32_bf16 v[72:75], v[212:215], v[188:191], v[72:75]
	v_mfma_f32_16x16x32_bf16 v[8:11], v[220:223], v[188:191], v[8:11]
	v_mfma_f32_16x16x32_bf16 v[64:67], v[212:215], v[198:201], v[64:67]
	v_mfma_f32_16x16x32_bf16 v[0:3], v[220:223], v[198:201], v[0:3]
	s_barrier
	s_add_i32 s34, 0, 0x18000
	v_add_u32_e32 v112, s34, v196
	ds_read_b128 v[96:99], v112
	ds_read_b128 v[100:103], v112 offset:1024
	ds_read_b128 v[104:107], v112 offset:2048
	ds_read_b128 v[158:161], v112 offset:3072
	s_add_u32 s62, s68, 0x80000
	s_addc_u32 s63, s69, 0
	s_mov_b32 m0, s73
	v_lshl_add_u64 v[112:113], s[62:63], 0, v[148:149]
	ds_read_b128 v[162:165], v207 offset:32768
	ds_read_b128 v[166:169], v207 offset:33792
	ds_read_b128 v[170:173], v207 offset:34816
	ds_read_b128 v[180:183], v207 offset:35840
	ds_read_b128 v[184:187], v207 offset:36864
	ds_read_b128 v[188:191], v207 offset:37888
	ds_read_b128 v[192:195], v207 offset:38912
	ds_read_b128 v[198:201], v207 offset:39936
	global_load_lds_dwordx4 v[112:113], off
	v_lshl_add_u64 v[112:113], s[62:63], 0, v[144:145]
	s_mov_b32 m0, s74
	s_nop 0
	global_load_lds_dwordx4 v[112:113], off
	s_waitcnt lgkmcnt(8)
	s_barrier
	s_waitcnt lgkmcnt(0)
	v_mfma_f32_16x16x32_bf16 v[138:141], v[96:99], v[162:165], v[138:141]
	v_mfma_f32_16x16x32_bf16 v[60:63], v[104:107], v[162:165], v[60:63]
	v_mfma_f32_16x16x32_bf16 v[134:137], v[96:99], v[170:173], v[134:137]
	v_mfma_f32_16x16x32_bf16 v[56:59], v[104:107], v[170:173], v[56:59]
	v_mfma_f32_16x16x32_bf16 v[130:133], v[96:99], v[184:187], v[130:133]
	v_mfma_f32_16x16x32_bf16 v[52:55], v[104:107], v[184:187], v[52:55]
	v_mfma_f32_16x16x32_bf16 v[126:129], v[96:99], v[192:195], v[126:129]
	v_mfma_f32_16x16x32_bf16 v[48:51], v[104:107], v[192:195], v[48:51]
	v_mfma_f32_16x16x32_bf16 v[138:141], v[100:103], v[166:169], v[138:141]
	v_mfma_f32_16x16x32_bf16 v[60:63], v[158:161], v[166:169], v[60:63]
	v_mfma_f32_16x16x32_bf16 v[134:137], v[100:103], v[180:183], v[134:137]
	v_mfma_f32_16x16x32_bf16 v[56:59], v[158:161], v[180:183], v[56:59]
	v_mfma_f32_16x16x32_bf16 v[130:133], v[100:103], v[188:191], v[130:133]
	v_mfma_f32_16x16x32_bf16 v[52:55], v[158:161], v[188:191], v[52:55]
	v_mfma_f32_16x16x32_bf16 v[126:129], v[100:103], v[198:201], v[126:129]
	v_mfma_f32_16x16x32_bf16 v[48:51], v[158:161], v[198:201], v[48:51]
	s_barrier
	s_add_i32 s35, 0, 0x1c000
	v_add_u32_e32 v112, s35, v196
	s_add_i32 s34, s34, s39
	ds_read_b128 v[208:211], v112
	ds_read_b128 v[212:215], v112 offset:1024
	ds_read_b128 v[216:219], v112 offset:2048
	ds_read_b128 v[220:223], v112 offset:3072
	v_lshl_add_u64 v[112:113], v[174:175], 0, s[40:41]
	s_mov_b32 m0, s34
	s_nop 0
	global_load_lds_dwordx4 v[112:113], off
	v_lshl_add_u64 v[112:113], v[224:225], 0, s[40:41]
	s_add_i32 m0, s34, 0x2000
	s_nop 0
	global_load_lds_dwordx4 v[112:113], off
	s_barrier
	s_waitcnt lgkmcnt(0)
	v_mfma_f32_16x16x32_bf16 v[122:125], v[208:211], v[162:165], v[122:125]
	v_mfma_f32_16x16x32_bf16 v[44:47], v[216:219], v[162:165], v[44:47]
	v_mfma_f32_16x16x32_bf16 v[112:115], v[208:211], v[170:173], v[114:117]
	v_mfma_f32_16x16x32_bf16 v[36:39], v[216:219], v[170:173], v[36:39]
	v_mfma_f32_16x16x32_bf16 v[118:121], v[208:211], v[184:187], v[118:121]
	v_mfma_f32_16x16x32_bf16 v[40:43], v[216:219], v[184:187], v[40:43]
	v_mfma_f32_16x16x32_bf16 v[108:111], v[208:211], v[192:195], v[108:111]
	v_mfma_f32_16x16x32_bf16 v[32:35], v[216:219], v[192:195], v[32:35]
	v_mfma_f32_16x16x32_bf16 v[122:125], v[212:215], v[166:169], v[122:125]
	v_mfma_f32_16x16x32_bf16 v[44:47], v[220:223], v[166:169], v[44:47]
	v_mfma_f32_16x16x32_bf16 v[114:117], v[212:215], v[180:183], v[112:115]
	v_mfma_f32_16x16x32_bf16 v[36:39], v[220:223], v[180:183], v[36:39]
	v_mfma_f32_16x16x32_bf16 v[118:121], v[212:215], v[188:191], v[118:121]
	v_mfma_f32_16x16x32_bf16 v[40:43], v[220:223], v[188:191], v[40:43]
	v_mfma_f32_16x16x32_bf16 v[110:113], v[212:215], v[198:201], v[108:111]
	v_mfma_f32_16x16x32_bf16 v[32:35], v[220:223], v[198:201], v[32:35]
	s_barrier
	s_mov_b32 m0, s76
	v_lshl_add_u64 v[108:109], v[226:227], 0, s[40:41]
	ds_read_b128 v[162:165], v207 offset:49152
	ds_read_b128 v[166:169], v207 offset:50176
	ds_read_b128 v[170:173], v207 offset:51200
	ds_read_b128 v[180:183], v207 offset:52224
	ds_read_b128 v[184:187], v207 offset:53248
	ds_read_b128 v[188:191], v207 offset:54272
	ds_read_b128 v[192:195], v207 offset:55296
	ds_read_b128 v[198:201], v207 offset:56320
	global_load_lds_dwordx4 v[108:109], off
	v_lshl_add_u64 v[108:109], v[228:229], 0, s[40:41]
	s_mov_b32 m0, s77
	s_nop 0
	global_load_lds_dwordx4 v[108:109], off
	s_barrier
	s_waitcnt lgkmcnt(0)
	v_mfma_f32_16x16x32_bf16 v[92:95], v[96:99], v[162:165], v[92:95]
	v_mfma_f32_16x16x32_bf16 v[28:31], v[104:107], v[162:165], v[28:31]
	v_mfma_f32_16x16x32_bf16 v[88:91], v[96:99], v[170:173], v[88:91]
	v_mfma_f32_16x16x32_bf16 v[24:27], v[104:107], v[170:173], v[24:27]
	v_mfma_f32_16x16x32_bf16 v[84:87], v[96:99], v[184:187], v[84:87]
	v_mfma_f32_16x16x32_bf16 v[20:23], v[104:107], v[184:187], v[20:23]
	v_mfma_f32_16x16x32_bf16 v[80:83], v[96:99], v[192:195], v[80:83]
	v_mfma_f32_16x16x32_bf16 v[16:19], v[104:107], v[192:195], v[16:19]
	v_mfma_f32_16x16x32_bf16 v[92:95], v[100:103], v[166:169], v[92:95]
	v_mfma_f32_16x16x32_bf16 v[28:31], v[158:161], v[166:169], v[28:31]
	v_mfma_f32_16x16x32_bf16 v[88:91], v[100:103], v[180:183], v[88:91]
	v_mfma_f32_16x16x32_bf16 v[24:27], v[158:161], v[180:183], v[24:27]
	v_mfma_f32_16x16x32_bf16 v[84:87], v[100:103], v[188:191], v[84:87]
	v_mfma_f32_16x16x32_bf16 v[20:23], v[158:161], v[188:191], v[20:23]
	v_mfma_f32_16x16x32_bf16 v[80:83], v[100:103], v[198:201], v[80:83]
	v_mfma_f32_16x16x32_bf16 v[16:19], v[158:161], v[198:201], v[16:19]
	s_barrier
	s_add_u32 s62, s66, 0x80080
	s_addc_u32 s63, s67, 0
	s_add_i32 s34, s35, s39
	v_lshl_add_u64 v[96:97], s[62:63], 0, v[146:147]
	s_mov_b32 m0, s34
	s_nop 0
	global_load_lds_dwordx4 v[96:97], off
	v_lshl_add_u64 v[96:97], s[62:63], 0, v[142:143]
	s_add_i32 m0, s34, 0x2000
	s_nop 0
	global_load_lds_dwordx4 v[96:97], off
	s_waitcnt vmcnt(6)
	s_barrier
	v_mfma_f32_16x16x32_bf16 v[76:79], v[208:211], v[162:165], v[76:79]
	v_mfma_f32_16x16x32_bf16 v[12:15], v[216:219], v[162:165], v[12:15]
	v_mfma_f32_16x16x32_bf16 v[68:71], v[208:211], v[170:173], v[68:71]
	v_mfma_f32_16x16x32_bf16 v[4:7], v[216:219], v[170:173], v[4:7]
	v_mfma_f32_16x16x32_bf16 v[72:75], v[208:211], v[184:187], v[72:75]
	v_mfma_f32_16x16x32_bf16 v[8:11], v[216:219], v[184:187], v[8:11]
	v_mfma_f32_16x16x32_bf16 v[64:67], v[208:211], v[192:195], v[64:67]
	v_mfma_f32_16x16x32_bf16 v[0:3], v[216:219], v[192:195], v[0:3]
	v_mfma_f32_16x16x32_bf16 v[76:79], v[212:215], v[166:169], v[76:79]
	v_mfma_f32_16x16x32_bf16 v[12:15], v[220:223], v[166:169], v[12:15]
	v_mfma_f32_16x16x32_bf16 v[68:71], v[212:215], v[180:183], v[68:71]
	v_mfma_f32_16x16x32_bf16 v[4:7], v[220:223], v[180:183], v[4:7]
	v_mfma_f32_16x16x32_bf16 v[72:75], v[212:215], v[188:191], v[72:75]
	v_mfma_f32_16x16x32_bf16 v[8:11], v[220:223], v[188:191], v[8:11]
	v_mfma_f32_16x16x32_bf16 v[64:67], v[212:215], v[198:201], v[64:67]
	v_mfma_f32_16x16x32_bf16 v[0:3], v[220:223], v[198:201], v[0:3]
	s_barrier
	s_add_i32 s83, s83, 2
	s_add_u32 s81, s81, 0x100
	s_addc_u32 s82, s82, 0
	s_cmp_gt_u32 s83, 29
	s_mov_b64 s[62:63], s[64:65]
	s_cbranch_scc0 .LBB0_173
	v_lshl_or_b32 v158, s70, 7, v150
	v_ashrrev_i32_e32 v159, 31, v158
	v_lshlrev_b64 v[96:97], 2, v[158:159]
	v_lshl_add_u64 v[98:99], s[30:31], 0, v[96:97]
	v_lshl_add_u64 v[100:101], s[46:47], 0, v[96:97]
	v_lshl_add_u64 v[102:103], s[24:25], 0, v[96:97]
	global_load_dwordx4 v[160:163], v[98:99], off
	global_load_dwordx4 v[170:173], v[100:101], off
	v_lshl_add_u64 v[98:99], s[42:43], 0, v[96:97]
	v_lshl_add_u64 v[100:101], s[48:49], 0, v[96:97]
	global_load_dwordx4 v[104:107], v[102:103], off
	global_load_dwordx4 v[164:167], v[98:99], off
	global_load_dwordx4 v[208:211], v[100:101], off
	v_lshl_add_u64 v[100:101], s[50:51], 0, v[96:97]
	global_load_dwordx4 v[212:215], v[100:101], off
	v_lshl_add_u64 v[98:99], s[26:27], 0, v[96:97]
	global_load_dwordx4 v[198:201], v[98:99], off
	v_lshl_add_u64 v[96:97], s[52:53], 0, v[96:97]
	global_load_dwordx4 v[216:219], v[96:97], off
	v_mov_b32_e32 v96, v177
	v_mov_b32_e32 v97, v177
	s_mov_b32 s62, 0xbf317218
	v_mov_b32_dpp v96, v126 row_ror:1 row_mask:0xf bank_mask:0xf
	v_mov_b32_dpp v97, v127 row_ror:1 row_mask:0xf bank_mask:0xf
	s_mov_b32 s34, 0xbfb8aa3b
	v_mov_b32_e32 v100, v177
	v_mov_b32_e32 v101, v177
	v_mov_b32_e32 v224, v177
	v_mov_b32_e32 v225, v177
	v_mov_b32_dpp v100, v138 row_ror:15 row_mask:0xf bank_mask:0xf
	v_mov_b32_dpp v101, v139 row_ror:15 row_mask:0xf bank_mask:0xf
	v_mov_b32_e32 v220, v177
	v_mov_b32_e32 v221, v177
	v_mov_b32_dpp v224, v112 row_ror:1 row_mask:0xf bank_mask:0xf
	v_mov_b32_dpp v225, v113 row_ror:1 row_mask:0xf bank_mask:0xf
	v_mov_b32_dpp v220, v128 row_ror:1 row_mask:0xf bank_mask:0xf
	v_mov_b32_dpp v221, v129 row_ror:1 row_mask:0xf bank_mask:0xf
	v_mov_b32_e32 v222, v177
	v_mov_b32_e32 v223, v177
	v_mov_b32_e32 v108, v177
	v_mov_b32_e32 v180, v177
	v_mov_b32_e32 v109, v177
	v_mov_b32_e32 v181, v177
	v_mov_b32_dpp v222, v140 row_ror:15 row_mask:0xf bank_mask:0xf
	v_mov_b32_dpp v223, v141 row_ror:15 row_mask:0xf bank_mask:0xf
	v_mov_b32_dpp v108, v110 row_ror:1 row_mask:0xf bank_mask:0xf
	v_mov_b32_dpp v180, v122 row_ror:15 row_mask:0xf bank_mask:0xf
	v_mov_b32_dpp v109, v111 row_ror:1 row_mask:0xf bank_mask:0xf
	v_mov_b32_dpp v181, v123 row_ror:15 row_mask:0xf bank_mask:0xf
	v_mov_b32_e32 v226, v177
	v_mov_b32_e32 v227, v177
	v_cmp_gt_i32_e32 vcc, 15, v151
	v_mov_b32_dpp v226, v124 row_ror:15 row_mask:0xf bank_mask:0xf
	v_mov_b32_dpp v227, v125 row_ror:15 row_mask:0xf bank_mask:0xf
	s_mov_b64 s[68:69], -1
	s_waitcnt vmcnt(0)
	v_pk_mul_f32 v[192:193], v[160:161], s[62:63] op_sel_hi:[1,0]
	v_pk_mul_f32 v[168:169], v[172:173], s[34:35] op_sel_hi:[1,0]
	v_pk_mul_f32 v[228:229], v[126:127], v[192:193]
	v_pk_mul_f32 v[194:195], v[162:163], s[62:63] op_sel_hi:[1,0]
	v_pk_mul_f32 v[186:187], v[104:105], s[62:63] op_sel_hi:[1,0]
	v_pk_mul_f32 v[188:189], v[166:167], s[62:63] op_sel_hi:[1,0]
	v_pk_mul_f32 v[172:173], v[210:211], s[34:35] op_sel_hi:[1,0]
	v_pk_mul_f32 v[96:97], v[186:187], v[96:97]
	v_pk_mul_f32 v[166:167], v[214:215], s[34:35] op_sel_hi:[1,0]
	v_pk_mul_f32 v[210:211], v[134:135], v[192:193]
	v_pk_mul_f32 v[214:215], v[130:131], v[192:193]
	v_pk_mul_f32 v[182:183], v[164:165], s[62:63] op_sel_hi:[1,0]
	v_pk_fma_f32 v[96:97], v[138:139], v[192:193], v[96:97]
	v_pk_fma_f32 v[210:211], v[138:139], v[186:187], v[210:211]
	v_pk_fma_f32 v[214:215], v[134:135], v[186:187], v[214:215]
	v_pk_fma_f32 v[228:229], v[130:131], v[186:187], v[228:229]
	v_pk_fma_f32 v[96:97], v[134:135], v[182:183], v[96:97]
	v_pk_fma_f32 v[210:211], v[130:131], v[182:183], v[210:211]
	v_pk_fma_f32 v[214:215], v[126:127], v[182:183], v[214:215]
	v_pk_fma_f32 v[100:101], v[182:183], v[100:101], v[228:229]
	v_pk_mul_f32 v[190:191], v[106:107], s[62:63] op_sel_hi:[1,0]
	v_pk_mul_f32 v[174:175], v[198:199], s[62:63] op_sel_hi:[1,0]
	v_pk_fma_f32 v[96:97], v[198:199], s[62:63], v[96:97] op_sel_hi:[1,0,1]
	v_pk_fma_f32 v[210:211], v[198:199], s[62:63], v[210:211] op_sel_hi:[1,0,1]
	v_pk_fma_f32 v[214:215], v[198:199], s[62:63], v[214:215] op_sel_hi:[1,0,1]
	v_pk_fma_f32 v[100:101], v[198:199], s[62:63], v[100:101] op_sel_hi:[1,0,1]
	v_pk_mul_f32 v[198:199], v[168:169], v[224:225]
	v_pk_mul_f32 v[164:165], v[170:171], s[34:35] op_sel_hi:[1,0]
	v_pk_mul_f32 v[170:171], v[208:209], s[34:35] op_sel_hi:[1,0]
	v_pk_mul_f32 v[162:163], v[212:213], s[34:35] op_sel_hi:[1,0]
	v_pk_mul_f32 v[104:105], v[190:191], v[220:221]
	v_pk_mul_f32 v[208:209], v[136:137], v[194:195]
	v_pk_mul_f32 v[212:213], v[132:133], v[194:195]
	v_pk_mul_f32 v[220:221], v[128:129], v[194:195]
	v_pk_fma_f32 v[198:199], v[124:125], v[172:173], v[198:199]
	v_pk_fma_f32 v[104:105], v[140:141], v[194:195], v[104:105]
	v_pk_fma_f32 v[208:209], v[140:141], v[190:191], v[208:209]
	v_pk_fma_f32 v[212:213], v[136:137], v[190:191], v[212:213]
	v_pk_fma_f32 v[220:221], v[132:133], v[190:191], v[220:221]
	v_pk_fma_f32 v[198:199], v[116:117], v[166:167], v[198:199]
	v_pk_mul_f32 v[232:233], v[110:111], v[170:171]
	v_pk_fma_f32 v[104:105], v[136:137], v[188:189], v[104:105]
	v_pk_fma_f32 v[208:209], v[132:133], v[188:189], v[208:209]
	v_pk_fma_f32 v[212:213], v[128:129], v[188:189], v[212:213]
	v_pk_fma_f32 v[220:221], v[188:189], v[222:223], v[220:221]
	v_pk_fma_f32 v[198:199], v[218:219], s[34:35], v[198:199] op_sel_hi:[1,0,1]
	v_pk_fma_f32 v[232:233], v[118:119], v[164:165], v[232:233]
	v_pk_mul_f32 v[184:185], v[200:201], s[62:63] op_sel_hi:[1,0]
	v_pk_fma_f32 v[104:105], v[200:201], s[62:63], v[104:105] op_sel_hi:[1,0,1]
	v_pk_fma_f32 v[208:209], v[200:201], s[62:63], v[208:209] op_sel_hi:[1,0,1]
	v_pk_fma_f32 v[212:213], v[200:201], s[62:63], v[212:213] op_sel_hi:[1,0,1]
	v_pk_fma_f32 v[200:201], v[200:201], s[62:63], v[220:221] op_sel_hi:[1,0,1]
	v_pk_mul_f32 v[108:109], v[164:165], v[108:109]
	v_pk_mul_f32 v[220:221], v[116:117], v[172:173]
	v_pk_mul_f32 v[222:223], v[114:115], v[170:171]
	v_pk_fma_f32 v[180:181], v[162:163], v[180:181], v[232:233]
	v_exp_f32_e32 v232, v198
	v_exp_f32_e32 v233, v199
	v_pk_fma_f32 v[108:109], v[122:123], v[170:171], v[108:109]
	v_pk_fma_f32 v[220:221], v[124:125], v[168:169], v[220:221]
	v_pk_fma_f32 v[222:223], v[122:123], v[164:165], v[222:223]
	v_pk_mul_f32 v[228:229], v[118:119], v[170:171]
	v_pk_fma_f32 v[108:109], v[114:115], v[162:163], v[108:109]
	v_pk_fma_f32 v[220:221], v[120:121], v[166:167], v[220:221]
	v_pk_fma_f32 v[222:223], v[118:119], v[162:163], v[222:223]
	v_pk_fma_f32 v[228:229], v[114:115], v[164:165], v[228:229]
	v_pk_mul_f32 v[230:231], v[112:113], v[172:173]
	v_pk_fma_f32 v[108:109], v[216:217], s[34:35], v[108:109] op_sel_hi:[1,0,1]
	v_pk_fma_f32 v[220:221], v[218:219], s[34:35], v[220:221] op_sel_hi:[1,0,1]
	v_pk_fma_f32 v[222:223], v[216:217], s[34:35], v[222:223] op_sel_hi:[1,0,1]
	v_pk_fma_f32 v[228:229], v[110:111], v[162:163], v[228:229]
	v_pk_fma_f32 v[230:231], v[120:121], v[168:169], v[230:231]
	v_pk_mul_f32 v[106:107], v[216:217], s[34:35] op_sel_hi:[1,0]
	v_pk_fma_f32 v[228:229], v[216:217], s[34:35], v[228:229] op_sel_hi:[1,0,1]
	v_pk_fma_f32 v[226:227], v[166:167], v[226:227], v[230:231]
	v_exp_f32_e32 v230, v108
	v_exp_f32_e32 v231, v109
	v_pk_fma_f32 v[180:181], v[216:217], s[34:35], v[180:181] op_sel_hi:[1,0,1]
	v_pk_add_f32 v[216:217], v[232:233], 1.0 op_sel_hi:[1,0]
	v_pk_mul_f32 v[104:105], v[104:105], v[198:199]
	v_pk_mul_f32 v[96:97], v[96:97], v[108:109]
	v_exp_f32_e32 v108, v222
	v_exp_f32_e32 v198, v220
	v_exp_f32_e32 v199, v221
	v_exp_f32_e32 v109, v223
	v_pk_mul_f32 v[224:225], v[120:121], v[172:173]
	v_rcp_f32_e32 v216, v216
	v_rcp_f32_e32 v217, v217
	v_pk_fma_f32 v[224:225], v[116:117], v[168:169], v[224:225]
	v_pk_add_f32 v[198:199], v[198:199], 1.0 op_sel_hi:[1,0]
	v_pk_fma_f32 v[224:225], v[112:113], v[166:167], v[224:225]
	v_pk_add_f32 v[108:109], v[108:109], 1.0 op_sel_hi:[1,0]
	v_pk_fma_f32 v[224:225], v[218:219], s[34:35], v[224:225] op_sel_hi:[1,0,1]
	v_pk_mul_f32 v[104:105], v[104:105], v[216:217]
	v_rcp_f32_e32 v108, v108
	v_rcp_f32_e32 v109, v109
	v_rcp_f32_e32 v198, v198
	v_rcp_f32_e32 v199, v199
	v_pk_mul_f32 v[208:209], v[208:209], v[220:221]
	v_exp_f32_e32 v216, v228
	v_exp_f32_e32 v220, v224
	v_exp_f32_e32 v221, v225
	v_exp_f32_e32 v217, v229
	v_pk_mul_f32 v[210:211], v[210:211], v[222:223]
	v_pk_mul_f32 v[160:161], v[218:219], s[34:35] op_sel_hi:[1,0]
	v_pk_fma_f32 v[218:219], v[218:219], s[34:35], v[226:227] op_sel_hi:[1,0,1]
	v_pk_mul_f32 v[198:199], v[208:209], v[198:199]
	v_pk_mul_f32 v[208:209], v[210:211], v[108:109]
	v_pk_add_f32 v[108:109], v[220:221], 1.0 op_sel_hi:[1,0]
	v_pk_add_f32 v[210:211], v[216:217], 1.0 op_sel_hi:[1,0]
	v_rcp_f32_e32 v108, v108
	v_rcp_f32_e32 v210, v210
	v_rcp_f32_e32 v211, v211
	v_rcp_f32_e32 v109, v109
	v_exp_f32_e32 v216, v180
	v_exp_f32_e32 v220, v218
	v_exp_f32_e32 v221, v219
	v_exp_f32_e32 v217, v181
	v_pk_add_f32 v[226:227], v[230:231], 1.0 op_sel_hi:[1,0]
	v_pk_mul_f32 v[212:213], v[212:213], v[224:225]
	v_pk_mul_f32 v[214:215], v[214:215], v[228:229]
	v_rcp_f32_e32 v226, v226
	v_rcp_f32_e32 v227, v227
	v_pk_mul_f32 v[212:213], v[212:213], v[108:109]
	v_pk_mul_f32 v[210:211], v[214:215], v[210:211]
	v_pk_add_f32 v[108:109], v[220:221], 1.0 op_sel_hi:[1,0]
	v_pk_add_f32 v[214:215], v[216:217], 1.0 op_sel_hi:[1,0]
	v_rcp_f32_e32 v108, v108
	v_rcp_f32_e32 v214, v214
	v_rcp_f32_e32 v109, v109
	v_rcp_f32_e32 v215, v215
	v_pk_mul_f32 v[96:97], v[96:97], v[226:227]
	v_pk_mul_f32 v[200:201], v[200:201], v[218:219]
	v_pk_mul_f32 v[100:101], v[100:101], v[180:181]
	v_pk_mul_f32 v[180:181], v[200:201], v[108:109]
	v_pk_mul_f32 v[200:201], v[100:101], v[214:215]
	v_cvt_pk_bf16_f32 v108, v96, v97
	v_cvt_pk_bf16_f32 v109, v104, v105
	v_cvt_pk_bf16_f32 v104, v208, v209
	v_cvt_pk_bf16_f32 v105, v198, v199
	v_cvt_pk_bf16_f32 v100, v210, v211
	v_cvt_pk_bf16_f32 v101, v212, v213
	s_nop 0
	v_cvt_pk_bf16_f32 v96, v200, v201
	v_cvt_pk_bf16_f32 v97, v180, v181
	s_and_saveexec_b64 s[62:63], vcc
	v_cmp_eq_u32_e32 vcc, 0, v151
	s_orn2_b64 s[68:69], vcc, exec
	s_or_b64 exec, exec, s[62:63]
	s_lshl_b32 s34, s79, 2
	s_lshl_b32 s62, s70, 8
	s_add_i32 s64, s34, s38
	s_ashr_i32 s63, s62, 31
	v_lshlrev_b32_e32 v176, 2, v150
	s_mov_b64 s[66:67], exec
	s_and_b64 s[68:69], s[66:67], s[68:69]
	v_mov_b32_e32 v198, 0xbf1f24be
	s_mov_b64 exec, s[68:69]
	s_cbranch_execz .LBB0_178
	s_ashr_i32 s65, s64, 31
	s_lshl_b64 s[68:69], s[64:65], 2
	v_or_b32_e32 v178, s68, v152
	v_mov_b64_e32 v[180:181], s[4:5]
	s_mov_b32 s29, 0xb000
	v_mad_u64_u32 v[180:181], s[70:71], v178, s29, v[180:181]
	v_mad_i32_i24 v181, s69, v204, v181
	v_lshl_add_u64 v[180:181], s[62:63], 2, v[180:181]
	v_lshl_add_u64 v[180:181], v[180:181], 0, v[176:177]
	v_cndmask_b32_e64 v133, v133, v141, s[8:9]
	v_cndmask_b32_e64 v132, v132, v140, s[8:9]
	v_cndmask_b32_e64 v131, v131, v139, s[8:9]
	v_cndmask_b32_e64 v130, v130, v138, s[8:9]
	v_cndmask_b32_e64 v118, v118, v122, s[8:9]
	v_cndmask_b32_e64 v121, v121, v125, s[8:9]
	v_cndmask_b32_e64 v120, v120, v124, s[8:9]
	v_cndmask_b32_e64 v119, v119, v123, s[8:9]
	global_store_dwordx4 v[180:181], v[130:133], off
	global_store_dwordx4 v[180:181], v[118:121], off offset:512
	v_cndmask_b32_e64 v125, v129, v137, s[8:9]
	v_cndmask_b32_e64 v124, v128, v136, s[8:9]
	v_add_co_u32_e32 v118, vcc, s29, v180
	v_cndmask_b32_e64 v123, v127, v135, s[8:9]
	v_cndmask_b32_e64 v122, v126, v134, s[8:9]
	v_addc_co_u32_e32 v119, vcc, 0, v181, vcc
	v_cndmask_b32_e64 v113, v113, v117, s[8:9]
	v_cndmask_b32_e64 v112, v112, v116, s[8:9]
	v_cndmask_b32_e64 v111, v111, v115, s[8:9]
	v_cndmask_b32_e64 v110, v110, v114, s[8:9]
	global_store_dwordx4 v[118:119], v[122:125], off
	global_store_dwordx4 v[118:119], v[110:113], off offset:512

.LBB0_264:
	s_add_i32 s61, s24, 2
	s_add_u32 s26, s8, 0x80
	s_addc_u32 s25, s9, 0
	s_add_i32 s29, 0, 0x10000
	v_add_u32_e32 v140, s29, v193
	ds_read_b128 v[128:131], v140
	ds_read_b128 v[132:135], v140 offset:1024
	ds_read_b128 v[136:139], v140 offset:2048
	ds_read_b128 v[140:143], v140 offset:3072
	s_cmp_eq_u32 s47, s24
	s_cselect_b32 s24, s20, s26
	s_cselect_b32 s25, s21, s25
	s_cselect_b32 s27, s11, s60
	s_cselect_b32 s26, s10, s59
	v_lshl_add_u64 v[180:181], s[8:9], 0, v[174:175]
	s_add_i32 m0, s33, 0xc000
	ds_read_b128 v[144:147], v195
	ds_read_b128 v[148:151], v195 offset:1024
	ds_read_b128 v[152:155], v195 offset:2048
	ds_read_b128 v[156:159], v195 offset:3072
	ds_read_b128 v[160:163], v195 offset:4096
	ds_read_b128 v[164:167], v195 offset:5120
	ds_read_b128 v[184:187], v195 offset:6144
	ds_read_b128 v[188:191], v195 offset:7168
	global_load_lds_dwordx4 v[180:181], off
	v_lshl_add_u64 v[180:181], s[8:9], 0, v[182:183]
	s_add_i32 m0, s33, 0xe000
	s_nop 0
	global_load_lds_dwordx4 v[180:181], off
	s_waitcnt lgkmcnt(8)
	s_barrier
	s_waitcnt lgkmcnt(0)
	v_mfma_f32_16x16x32_bf16 v[124:127], v[128:131], v[144:147], v[124:127]
	v_mfma_f32_16x16x32_bf16 v[120:123], v[136:139], v[144:147], v[120:123]
	v_mfma_f32_16x16x32_bf16 v[108:111], v[128:131], v[152:155], v[108:111]
	v_mfma_f32_16x16x32_bf16 v[104:107], v[136:139], v[152:155], v[104:107]
	v_mfma_f32_16x16x32_bf16 v[92:95], v[128:131], v[160:163], v[92:95]
	v_mfma_f32_16x16x32_bf16 v[88:91], v[136:139], v[160:163], v[88:91]
	v_mfma_f32_16x16x32_bf16 v[76:79], v[128:131], v[184:187], v[76:79]
	v_mfma_f32_16x16x32_bf16 v[72:75], v[136:139], v[184:187], v[72:75]
	v_mfma_f32_16x16x32_bf16 v[124:127], v[132:135], v[148:151], v[124:127]
	v_mfma_f32_16x16x32_bf16 v[120:123], v[140:143], v[148:151], v[120:123]
	v_mfma_f32_16x16x32_bf16 v[108:111], v[132:135], v[156:159], v[108:111]
	v_mfma_f32_16x16x32_bf16 v[104:107], v[140:143], v[156:159], v[104:107]
	v_mfma_f32_16x16x32_bf16 v[92:95], v[132:135], v[164:167], v[92:95]
	v_mfma_f32_16x16x32_bf16 v[88:91], v[140:143], v[164:167], v[88:91]
	v_mfma_f32_16x16x32_bf16 v[76:79], v[132:135], v[188:191], v[76:79]
	v_mfma_f32_16x16x32_bf16 v[72:75], v[140:143], v[188:191], v[72:75]
	s_barrier
	s_add_i32 s34, 0, 0x14000
	s_add_i32 s29, s29, s31
	v_add_u32_e32 v178, s34, v193
	v_lshl_add_u64 v[180:181], s[26:27], 0, v[176:177]
	s_mov_b32 m0, s29
	ds_read_b128 v[196:199], v178
	ds_read_b128 v[208:211], v178 offset:1024
	ds_read_b128 v[212:215], v178 offset:2048
	ds_read_b128 v[216:219], v178 offset:3072
	global_load_lds_dwordx4 v[180:181], off
	v_lshl_add_u64 v[200:201], s[26:27], 0, v[168:169]
	s_add_i32 m0, s29, 0x2000
	s_nop 0
	global_load_lds_dwordx4 v[200:201], off
	s_barrier
	s_waitcnt lgkmcnt(0)
	v_mfma_f32_16x16x32_bf16 v[116:119], v[196:199], v[144:147], v[116:119]
	v_mfma_f32_16x16x32_bf16 v[112:115], v[212:215], v[144:147], v[112:115]
	v_mfma_f32_16x16x32_bf16 v[100:103], v[196:199], v[152:155], v[100:103]
	v_mfma_f32_16x16x32_bf16 v[96:99], v[212:215], v[152:155], v[96:99]
	v_mfma_f32_16x16x32_bf16 v[84:87], v[196:199], v[160:163], v[84:87]
	v_mfma_f32_16x16x32_bf16 v[80:83], v[212:215], v[160:163], v[80:83]
	v_mfma_f32_16x16x32_bf16 v[68:71], v[196:199], v[184:187], v[68:71]
	v_mfma_f32_16x16x32_bf16 v[64:67], v[212:215], v[184:187], v[64:67]
	v_mfma_f32_16x16x32_bf16 v[116:119], v[208:211], v[148:151], v[116:119]
	v_mfma_f32_16x16x32_bf16 v[112:115], v[216:219], v[148:151], v[112:115]
	v_mfma_f32_16x16x32_bf16 v[100:103], v[208:211], v[156:159], v[100:103]
	v_mfma_f32_16x16x32_bf16 v[96:99], v[216:219], v[156:159], v[96:99]
	v_mfma_f32_16x16x32_bf16 v[84:87], v[208:211], v[164:167], v[84:87]
	v_mfma_f32_16x16x32_bf16 v[80:83], v[216:219], v[164:167], v[80:83]
	v_mfma_f32_16x16x32_bf16 v[68:71], v[208:211], v[188:191], v[68:71]
	v_mfma_f32_16x16x32_bf16 v[64:67], v[216:219], v[188:191], v[64:67]
	s_barrier
	s_mov_b32 m0, s33
	v_lshl_add_u64 v[220:221], s[24:25], 0, v[172:173]
	ds_read_b128 v[144:147], v195 offset:16384
	ds_read_b128 v[148:151], v195 offset:17408
	ds_read_b128 v[152:155], v195 offset:18432
	ds_read_b128 v[156:159], v195 offset:19456
	ds_read_b128 v[160:163], v195 offset:20480
	ds_read_b128 v[164:167], v195 offset:21504
	ds_read_b128 v[184:187], v195 offset:22528
	ds_read_b128 v[188:191], v195 offset:23552
	global_load_lds_dwordx4 v[220:221], off
	v_lshl_add_u64 v[222:223], s[24:25], 0, v[170:171]
	s_mov_b32 m0, s37
	s_nop 0
	global_load_lds_dwordx4 v[222:223], off
	s_barrier
	s_waitcnt lgkmcnt(0)
	v_mfma_f32_16x16x32_bf16 v[60:63], v[128:131], v[144:147], v[60:63]
	v_mfma_f32_16x16x32_bf16 v[56:59], v[136:139], v[144:147], v[56:59]
	v_mfma_f32_16x16x32_bf16 v[44:47], v[128:131], v[152:155], v[44:47]
	v_mfma_f32_16x16x32_bf16 v[40:43], v[136:139], v[152:155], v[40:43]
	v_mfma_f32_16x16x32_bf16 v[28:31], v[128:131], v[160:163], v[28:31]
	v_mfma_f32_16x16x32_bf16 v[24:27], v[136:139], v[160:163], v[24:27]
	v_mfma_f32_16x16x32_bf16 v[12:15], v[128:131], v[184:187], v[12:15]
	v_mfma_f32_16x16x32_bf16 v[8:11], v[136:139], v[184:187], v[8:11]
	v_mfma_f32_16x16x32_bf16 v[60:63], v[132:135], v[148:151], v[60:63]
	v_mfma_f32_16x16x32_bf16 v[56:59], v[140:143], v[148:151], v[56:59]
	v_mfma_f32_16x16x32_bf16 v[44:47], v[132:135], v[156:159], v[44:47]
	v_mfma_f32_16x16x32_bf16 v[40:43], v[140:143], v[156:159], v[40:43]
	v_mfma_f32_16x16x32_bf16 v[28:31], v[132:135], v[164:167], v[28:31]
	v_mfma_f32_16x16x32_bf16 v[24:27], v[140:143], v[164:167], v[24:27]
	v_mfma_f32_16x16x32_bf16 v[12:15], v[132:135], v[188:191], v[12:15]
	v_mfma_f32_16x16x32_bf16 v[8:11], v[140:143], v[188:191], v[8:11]
	s_barrier
	s_add_u32 s26, s26, s44
	s_addc_u32 s27, s27, 0
	s_add_i32 s29, s34, s31
	v_lshl_add_u64 v[224:225], s[26:27], 0, v[176:177]
	s_mov_b32 m0, s29
	v_lshl_add_u64 v[226:227], s[26:27], 0, v[168:169]
	global_load_lds_dwordx4 v[224:225], off
	s_add_i32 m0, s29, 0x2000
	s_nop 0
	global_load_lds_dwordx4 v[226:227], off
	s_waitcnt vmcnt(6)
	s_barrier
	v_mfma_f32_16x16x32_bf16 v[52:55], v[196:199], v[144:147], v[52:55]
	v_mfma_f32_16x16x32_bf16 v[48:51], v[212:215], v[144:147], v[48:51]
	v_mfma_f32_16x16x32_bf16 v[36:39], v[196:199], v[152:155], v[36:39]
	v_mfma_f32_16x16x32_bf16 v[32:35], v[212:215], v[152:155], v[32:35]
	v_mfma_f32_16x16x32_bf16 v[20:23], v[196:199], v[160:163], v[20:23]
	v_mfma_f32_16x16x32_bf16 v[16:19], v[212:215], v[160:163], v[16:19]
	v_mfma_f32_16x16x32_bf16 v[4:7], v[196:199], v[184:187], v[4:7]
	v_mfma_f32_16x16x32_bf16 v[0:3], v[212:215], v[184:187], v[0:3]
	v_mfma_f32_16x16x32_bf16 v[52:55], v[208:211], v[148:151], v[52:55]
	v_mfma_f32_16x16x32_bf16 v[48:51], v[216:219], v[148:151], v[48:51]
	v_mfma_f32_16x16x32_bf16 v[36:39], v[208:211], v[156:159], v[36:39]
	v_mfma_f32_16x16x32_bf16 v[32:35], v[216:219], v[156:159], v[32:35]
	v_mfma_f32_16x16x32_bf16 v[20:23], v[208:211], v[164:167], v[20:23]
	v_mfma_f32_16x16x32_bf16 v[16:19], v[216:219], v[164:167], v[16:19]
	v_mfma_f32_16x16x32_bf16 v[4:7], v[208:211], v[188:191], v[4:7]
	v_mfma_f32_16x16x32_bf16 v[0:3], v[216:219], v[188:191], v[0:3]
	s_barrier
	s_add_i32 s26, 0, 0x18000
	v_add_u32_e32 v140, s26, v193
	ds_read_b128 v[128:131], v140
	ds_read_b128 v[132:135], v140 offset:1024
	ds_read_b128 v[136:139], v140 offset:2048
	ds_read_b128 v[140:143], v140 offset:3072
	s_add_u32 s24, s24, s44
	s_addc_u32 s25, s25, 0
	s_mov_b32 m0, s38
	v_lshl_add_u64 v[196:197], s[24:25], 0, v[172:173]
	ds_read_b128 v[144:147], v195 offset:32768
	ds_read_b128 v[148:151], v195 offset:33792
	ds_read_b128 v[152:155], v195 offset:34816
	ds_read_b128 v[156:159], v195 offset:35840
	ds_read_b128 v[160:163], v195 offset:36864
	ds_read_b128 v[164:167], v195 offset:37888
	ds_read_b128 v[184:187], v195 offset:38912
	ds_read_b128 v[188:191], v195 offset:39936
	global_load_lds_dwordx4 v[196:197], off
	v_lshl_add_u64 v[196:197], s[24:25], 0, v[170:171]
	s_mov_b32 m0, s39
	s_nop 0
	global_load_lds_dwordx4 v[196:197], off
	s_waitcnt lgkmcnt(8)
	s_barrier
	s_waitcnt lgkmcnt(0)
	v_mfma_f32_16x16x32_bf16 v[124:127], v[128:131], v[144:147], v[124:127]
	v_mfma_f32_16x16x32_bf16 v[120:123], v[136:139], v[144:147], v[120:123]
	v_mfma_f32_16x16x32_bf16 v[108:111], v[128:131], v[152:155], v[108:111]
	v_mfma_f32_16x16x32_bf16 v[104:107], v[136:139], v[152:155], v[104:107]
	v_mfma_f32_16x16x32_bf16 v[92:95], v[128:131], v[160:163], v[92:95]
	v_mfma_f32_16x16x32_bf16 v[88:91], v[136:139], v[160:163], v[88:91]
	v_mfma_f32_16x16x32_bf16 v[76:79], v[128:131], v[184:187], v[76:79]
	v_mfma_f32_16x16x32_bf16 v[72:75], v[136:139], v[184:187], v[72:75]
	v_mfma_f32_16x16x32_bf16 v[124:127], v[132:135], v[148:151], v[124:127]
	v_mfma_f32_16x16x32_bf16 v[120:123], v[140:143], v[148:151], v[120:123]
	v_mfma_f32_16x16x32_bf16 v[108:111], v[132:135], v[156:159], v[108:111]
	v_mfma_f32_16x16x32_bf16 v[104:107], v[140:143], v[156:159], v[104:107]
	v_mfma_f32_16x16x32_bf16 v[92:95], v[132:135], v[164:167], v[92:95]
	v_mfma_f32_16x16x32_bf16 v[88:91], v[140:143], v[164:167], v[88:91]
	v_mfma_f32_16x16x32_bf16 v[76:79], v[132:135], v[188:191], v[76:79]
	v_mfma_f32_16x16x32_bf16 v[72:75], v[140:143], v[188:191], v[72:75]
	s_barrier
	s_add_i32 s24, 0, 0x1c000
	s_add_i32 s25, s26, s31
	v_add_u32_e32 v178, s24, v193
	v_lshl_add_u64 v[180:181], v[180:181], 0, s[40:41]
	s_mov_b32 m0, s25
	ds_read_b128 v[196:199], v178
	ds_read_b128 v[208:211], v178 offset:1024
	ds_read_b128 v[212:215], v178 offset:2048
	ds_read_b128 v[216:219], v178 offset:3072
	global_load_lds_dwordx4 v[180:181], off
	v_lshl_add_u64 v[180:181], v[200:201], 0, s[40:41]
	s_add_i32 m0, s25, 0x2000
	s_nop 0
	global_load_lds_dwordx4 v[180:181], off
	s_barrier
	s_waitcnt lgkmcnt(0)
	v_mfma_f32_16x16x32_bf16 v[116:119], v[196:199], v[144:147], v[116:119]
	v_mfma_f32_16x16x32_bf16 v[112:115], v[212:215], v[144:147], v[112:115]
	v_mfma_f32_16x16x32_bf16 v[100:103], v[196:199], v[152:155], v[100:103]
	v_mfma_f32_16x16x32_bf16 v[96:99], v[212:215], v[152:155], v[96:99]
	v_mfma_f32_16x16x32_bf16 v[84:87], v[196:199], v[160:163], v[84:87]
	v_mfma_f32_16x16x32_bf16 v[80:83], v[212:215], v[160:163], v[80:83]
	v_mfma_f32_16x16x32_bf16 v[68:71], v[196:199], v[184:187], v[68:71]
	v_mfma_f32_16x16x32_bf16 v[64:67], v[212:215], v[184:187], v[64:67]
	v_mfma_f32_16x16x32_bf16 v[116:119], v[208:211], v[148:151], v[116:119]
	v_mfma_f32_16x16x32_bf16 v[112:115], v[216:219], v[148:151], v[112:115]
	v_mfma_f32_16x16x32_bf16 v[100:103], v[208:211], v[156:159], v[100:103]
	v_mfma_f32_16x16x32_bf16 v[96:99], v[216:219], v[156:159], v[96:99]
	v_mfma_f32_16x16x32_bf16 v[84:87], v[208:211], v[164:167], v[84:87]
	v_mfma_f32_16x16x32_bf16 v[80:83], v[216:219], v[164:167], v[80:83]
	v_mfma_f32_16x16x32_bf16 v[68:71], v[208:211], v[188:191], v[68:71]
	v_mfma_f32_16x16x32_bf16 v[64:67], v[216:219], v[188:191], v[64:67]
	s_barrier
	s_mov_b32 m0, s43
	v_lshl_add_u64 v[180:181], v[220:221], 0, s[40:41]
	ds_read_b128 v[144:147], v195 offset:49152
	ds_read_b128 v[148:151], v195 offset:50176
	ds_read_b128 v[152:155], v195 offset:51200
	ds_read_b128 v[156:159], v195 offset:52224
	ds_read_b128 v[160:163], v195 offset:53248
	ds_read_b128 v[164:167], v195 offset:54272
	ds_read_b128 v[184:187], v195 offset:55296
	ds_read_b128 v[188:191], v195 offset:56320
	global_load_lds_dwordx4 v[180:181], off
	v_lshl_add_u64 v[180:181], v[222:223], 0, s[40:41]
	s_mov_b32 m0, s46
	s_nop 0
	global_load_lds_dwordx4 v[180:181], off
	s_barrier
	s_waitcnt lgkmcnt(0)
	v_mfma_f32_16x16x32_bf16 v[60:63], v[128:131], v[144:147], v[60:63]
	v_mfma_f32_16x16x32_bf16 v[56:59], v[136:139], v[144:147], v[56:59]
	v_mfma_f32_16x16x32_bf16 v[44:47], v[128:131], v[152:155], v[44:47]
	v_mfma_f32_16x16x32_bf16 v[40:43], v[136:139], v[152:155], v[40:43]
	v_mfma_f32_16x16x32_bf16 v[28:31], v[128:131], v[160:163], v[28:31]
	v_mfma_f32_16x16x32_bf16 v[24:27], v[136:139], v[160:163], v[24:27]
	v_mfma_f32_16x16x32_bf16 v[12:15], v[128:131], v[184:187], v[12:15]
	v_mfma_f32_16x16x32_bf16 v[8:11], v[136:139], v[184:187], v[8:11]
	v_mfma_f32_16x16x32_bf16 v[60:63], v[132:135], v[148:151], v[60:63]
	v_mfma_f32_16x16x32_bf16 v[56:59], v[140:143], v[148:151], v[56:59]
	v_mfma_f32_16x16x32_bf16 v[44:47], v[132:135], v[156:159], v[44:47]
	v_mfma_f32_16x16x32_bf16 v[40:43], v[140:143], v[156:159], v[40:43]
	v_mfma_f32_16x16x32_bf16 v[28:31], v[132:135], v[164:167], v[28:31]
	v_mfma_f32_16x16x32_bf16 v[24:27], v[140:143], v[164:167], v[24:27]
	v_mfma_f32_16x16x32_bf16 v[12:15], v[132:135], v[188:191], v[12:15]
	v_mfma_f32_16x16x32_bf16 v[8:11], v[140:143], v[188:191], v[8:11]
	s_barrier
	s_add_i32 s24, s24, s31
	v_lshl_add_u64 v[128:129], v[224:225], 0, s[40:41]
	s_mov_b32 m0, s24
	s_nop 0
	global_load_lds_dwordx4 v[128:129], off
	v_lshl_add_u64 v[128:129], v[226:227], 0, s[40:41]
	s_add_i32 m0, s24, 0x2000
	s_nop 0
	global_load_lds_dwordx4 v[128:129], off
	s_waitcnt vmcnt(6)
	s_barrier
	v_mfma_f32_16x16x32_bf16 v[52:55], v[196:199], v[144:147], v[52:55]
	v_mfma_f32_16x16x32_bf16 v[48:51], v[212:215], v[144:147], v[48:51]
	v_mfma_f32_16x16x32_bf16 v[36:39], v[196:199], v[152:155], v[36:39]
	v_mfma_f32_16x16x32_bf16 v[32:35], v[212:215], v[152:155], v[32:35]
	v_mfma_f32_16x16x32_bf16 v[20:23], v[196:199], v[160:163], v[20:23]
	v_mfma_f32_16x16x32_bf16 v[16:19], v[212:215], v[160:163], v[16:19]
	v_mfma_f32_16x16x32_bf16 v[4:7], v[196:199], v[184:187], v[4:7]
	v_mfma_f32_16x16x32_bf16 v[0:3], v[212:215], v[184:187], v[0:3]
	v_mfma_f32_16x16x32_bf16 v[52:55], v[208:211], v[148:151], v[52:55]
	v_mfma_f32_16x16x32_bf16 v[48:51], v[216:219], v[148:151], v[48:51]
	v_mfma_f32_16x16x32_bf16 v[36:39], v[208:211], v[156:159], v[36:39]
	v_mfma_f32_16x16x32_bf16 v[32:35], v[216:219], v[156:159], v[32:35]
	v_mfma_f32_16x16x32_bf16 v[20:23], v[208:211], v[164:167], v[20:23]
	v_mfma_f32_16x16x32_bf16 v[16:19], v[216:219], v[164:167], v[16:19]
	v_mfma_f32_16x16x32_bf16 v[4:7], v[208:211], v[188:191], v[4:7]
	v_mfma_f32_16x16x32_bf16 v[0:3], v[216:219], v[188:191], v[0:3]
	s_barrier
	s_add_u32 s59, s59, 0x100
	s_addc_u32 s60, s60, 0
	s_add_u32 s8, s8, 0x100
	s_addc_u32 s9, s9, 0
	s_cmp_ge_u32 s61, s42
	s_mov_b32 s24, s61
	s_cbranch_scc0 .LBB0_264
	s_sub_i32 s8, s57, 32
	s_lshr_b32 s8, s8, 3
	s_cmp_lt_i32 s57, 32
	s_cselect_b32 s26, 8, s8
	v_readlane_b32 s8, v255, 40
	v_readlane_b32 s9, v255, 41
	s_load_dwordx16 s[60:75], s[8:9], 0x0
	v_lshl_or_b32 v184, s58, 8, v194
	v_ashrrev_i32_e32 v185, 31, v184
	v_lshlrev_b64 v[128:129], 2, v[184:185]
	v_lshl_add_u32 v186, s57, 8, v192
	s_waitcnt lgkmcnt(0)
	s_cselect_b32 s24, s60, s50
	s_cselect_b32 s25, s61, s51
	s_add_i32 s8, s26, s53
	s_mul_hi_u32 s9, s8, 0xc000
	s_mul_i32 s8, s8, 0xc000
	s_add_u32 s8, s48, s8
	s_addc_u32 s9, s49, s9
	s_add_i32 s26, s54, s26
	s_mul_hi_u32 s27, s26, 0xc000
	s_mul_i32 s26, s26, 0xc000
	s_add_u32 s26, s48, s26
	s_addc_u32 s27, s49, s27
	v_lshl_add_u64 v[132:133], s[8:9], 0, v[128:129]
	v_lshl_add_u64 v[140:141], s[26:27], 0, v[128:129]
	global_load_dwordx4 v[144:147], v[132:133], off offset:16
	global_load_dwordx4 v[152:155], v[132:133], off
	global_load_dwordx4 v[148:151], v[140:141], off offset:16
	global_load_dwordx4 v[156:159], v[140:141], off
	global_load_dwordx4 v[128:131], v[132:133], off offset:528
	global_load_dwordx4 v[136:139], v[132:133], off offset:512
	s_nop 0
	global_load_dwordx4 v[132:135], v[140:141], off offset:528
	s_nop 0
	global_load_dwordx4 v[140:143], v[140:141], off offset:512
	v_lshl_add_u32 v196, v186, 11, v184
	v_lshlrev_b32_e32 v197, 2, v196
	v_lshlrev_b32_e32 v196, 1, v196
	s_and_b64 vcc, exec, s[4:5]
	s_cbranch_vccnz .Lres_f32
	global_load_dwordx4 v[164:167], v196, s[12:13]
	global_load_dwordx4 v[184:187], v196, s[12:13] offset:256
	s_add_u32 s62, s12, 0x10000
	s_addc_u32 s63, s13, 0
	global_load_dwordx4 v[188:191], v196, s[62:63]
	s_add_u32 s62, s12, 0x10000
	s_addc_u32 s63, s13, 0
	global_load_dwordx4 v[208:211], v196, s[62:63] offset:256
	s_add_u32 s62, s12, 0x20000
	s_addc_u32 s63, s13, 0
	global_load_dwordx4 v[212:215], v196, s[62:63]
	s_add_u32 s62, s12, 0x20000
	s_addc_u32 s63, s13, 0
	global_load_dwordx4 v[216:219], v196, s[62:63] offset:256
	s_add_u32 s62, s12, 0x30000
	s_addc_u32 s63, s13, 0
	global_load_dwordx4 v[220:223], v196, s[62:63]
	s_add_u32 s62, s12, 0x30000
	s_addc_u32 s63, s13, 0
	global_load_dwordx4 v[224:227], v196, s[62:63] offset:256
	s_waitcnt vmcnt(8)
	v_pk_add_f32 v[146:147], v[146:147], v[150:151]
	v_pk_add_f32 v[144:145], v[144:145], v[148:149]
	v_pk_add_f32 v[154:155], v[154:155], v[158:159]
	v_pk_add_f32 v[152:153], v[152:153], v[156:157]
	v_pk_add_f32 v[136:137], v[136:137], v[140:141]
	v_pk_add_f32 v[130:131], v[130:131], v[134:135]
	v_pk_add_f32 v[128:129], v[128:129], v[132:133]
	v_pk_add_f32 v[138:139], v[138:139], v[142:143]
	s_add_u32 s62, s12, 0x80000
	s_addc_u32 s63, s13, 0
	global_load_dwordx4 v[148:151], v196, s[62:63]
	s_add_u32 s62, s12, 0x80000
	s_addc_u32 s63, s13, 0
	global_load_dwordx4 v[156:159], v196, s[62:63] offset:256
	s_add_u32 s62, s12, 0x90000
	s_addc_u32 s63, s13, 0
	global_load_dwordx4 v[132:135], v196, s[62:63]
	s_add_u32 s62, s12, 0x90000
	s_addc_u32 s63, s13, 0
	global_load_dwordx4 v[140:143], v196, s[62:63] offset:256
	s_waitcnt vmcnt(11)
	v_lshlrev_b32_e32 v160, 16, v164
	v_and_b32_e32 v161, 0xffff0000, v164
	v_lshlrev_b32_e32 v162, 16, v165
	v_and_b32_e32 v163, 0xffff0000, v165
	v_lshlrev_b32_e32 v164, 16, v166
	v_and_b32_e32 v165, 0xffff0000, v166
	v_lshlrev_b32_e32 v166, 16, v167
	v_and_b32_e32 v167, 0xffff0000, v167
	v_pk_fma_f32 v[124:125], v[124:125], v[152:153], v[160:161]
	v_pk_fma_f32 v[126:127], v[126:127], v[154:155], v[162:163]
	v_pk_fma_f32 v[120:121], v[120:121], v[144:145], v[164:165]
	v_pk_fma_f32 v[122:123], v[122:123], v[146:147], v[166:167]
	s_add_u32 s62, s12, 0xa0000
	s_addc_u32 s63, s13, 0
	global_load_dwordx4 v[164:167], v196, s[62:63]
	v_cvt_pk_bf16_f32 v124, v124, v125
	v_cvt_pk_bf16_f32 v125, v126, v127
	v_cvt_pk_bf16_f32 v126, v120, v121
	v_cvt_pk_bf16_f32 v127, v122, v123
	global_store_dwordx4 v196, v[124:127], s[12:13]
	s_waitcnt vmcnt(12)
	v_lshlrev_b32_e32 v160, 16, v184
	v_and_b32_e32 v161, 0xffff0000, v184
	v_lshlrev_b32_e32 v162, 16, v185
	v_and_b32_e32 v163, 0xffff0000, v185
	v_lshlrev_b32_e32 v184, 16, v186
	v_and_b32_e32 v185, 0xffff0000, v186
	v_lshlrev_b32_e32 v186, 16, v187
	v_and_b32_e32 v187, 0xffff0000, v187
	v_pk_fma_f32 v[116:117], v[116:117], v[136:137], v[160:161]
	v_pk_fma_f32 v[118:119], v[118:119], v[138:139], v[162:163]
	v_pk_fma_f32 v[112:113], v[112:113], v[128:129], v[184:185]
	v_pk_fma_f32 v[114:115], v[114:115], v[130:131], v[186:187]
	s_add_u32 s62, s12, 0xa0000
	s_addc_u32 s63, s13, 0
	global_load_dwordx4 v[184:187], v196, s[62:63] offset:256
	v_cvt_pk_bf16_f32 v116, v116, v117
	v_cvt_pk_bf16_f32 v117, v118, v119
	v_cvt_pk_bf16_f32 v118, v112, v113
	v_cvt_pk_bf16_f32 v119, v114, v115
	global_store_dwordx4 v196, v[116:119], s[12:13] offset:256
	s_waitcnt vmcnt(13)
	v_lshlrev_b32_e32 v160, 16, v188
	v_and_b32_e32 v161, 0xffff0000, v188
	v_lshlrev_b32_e32 v162, 16, v189
	v_and_b32_e32 v163, 0xffff0000, v189
	v_lshlrev_b32_e32 v188, 16, v190
	v_and_b32_e32 v189, 0xffff0000, v190
	v_lshlrev_b32_e32 v190, 16, v191
	v_and_b32_e32 v191, 0xffff0000, v191
	v_pk_fma_f32 v[108:109], v[108:109], v[152:153], v[160:161]
	v_pk_fma_f32 v[110:111], v[110:111], v[154:155], v[162:163]
	v_pk_fma_f32 v[104:105], v[104:105], v[144:145], v[188:189]
	v_pk_fma_f32 v[106:107], v[106:107], v[146:147], v[190:191]
	s_add_u32 s62, s12, 0xb0000
	s_addc_u32 s63, s13, 0
	global_load_dwordx4 v[188:191], v196, s[62:63]
	v_cvt_pk_bf16_f32 v108, v108, v109
	v_cvt_pk_bf16_f32 v109, v110, v111
	v_cvt_pk_bf16_f32 v110, v104, v105
	v_cvt_pk_bf16_f32 v111, v106, v107
	s_add_u32 s64, s12, 0x10000
	s_addc_u32 s65, s13, 0
	global_store_dwordx4 v196, v[108:111], s[64:65]
	s_waitcnt vmcnt(14)
	v_lshlrev_b32_e32 v160, 16, v208
	v_and_b32_e32 v161, 0xffff0000, v208
	v_lshlrev_b32_e32 v162, 16, v209
	v_and_b32_e32 v163, 0xffff0000, v209
	v_lshlrev_b32_e32 v208, 16, v210
	v_and_b32_e32 v209, 0xffff0000, v210
	v_lshlrev_b32_e32 v210, 16, v211
	v_and_b32_e32 v211, 0xffff0000, v211
	v_pk_fma_f32 v[100:101], v[100:101], v[136:137], v[160:161]
	v_pk_fma_f32 v[102:103], v[102:103], v[138:139], v[162:163]
	v_pk_fma_f32 v[96:97], v[96:97], v[128:129], v[208:209]
	v_pk_fma_f32 v[98:99], v[98:99], v[130:131], v[210:211]
	s_add_u32 s62, s12, 0xb0000
	s_addc_u32 s63, s13, 0
	global_load_dwordx4 v[208:211], v196, s[62:63] offset:256
	v_cvt_pk_bf16_f32 v100, v100, v101
	v_cvt_pk_bf16_f32 v101, v102, v103
	v_cvt_pk_bf16_f32 v102, v96, v97
	v_cvt_pk_bf16_f32 v103, v98, v99
	s_add_u32 s64, s12, 0x10000
	s_addc_u32 s65, s13, 0
	global_store_dwordx4 v196, v[100:103], s[64:65] offset:256
	s_waitcnt vmcnt(15)
	v_lshlrev_b32_e32 v160, 16, v212
	v_and_b32_e32 v161, 0xffff0000, v212
	v_lshlrev_b32_e32 v162, 16, v213
	v_and_b32_e32 v163, 0xffff0000, v213
	v_lshlrev_b32_e32 v212, 16, v214
	v_and_b32_e32 v213, 0xffff0000, v214
	v_lshlrev_b32_e32 v214, 16, v215
	v_and_b32_e32 v215, 0xffff0000, v215
	v_pk_fma_f32 v[92:93], v[92:93], v[152:153], v[160:161]
	v_pk_fma_f32 v[94:95], v[94:95], v[154:155], v[162:163]
	v_pk_fma_f32 v[88:89], v[88:89], v[144:145], v[212:213]
	v_pk_fma_f32 v[90:91], v[90:91], v[146:147], v[214:215]
	v_cvt_pk_bf16_f32 v92, v92, v93
	v_cvt_pk_bf16_f32 v93, v94, v95
	v_cvt_pk_bf16_f32 v94, v88, v89
	v_cvt_pk_bf16_f32 v95, v90, v91
	s_add_u32 s64, s12, 0x20000
	s_addc_u32 s65, s13, 0
	global_store_dwordx4 v196, v[92:95], s[64:65]
	s_waitcnt vmcnt(15)
	v_lshlrev_b32_e32 v160, 16, v216
	v_and_b32_e32 v161, 0xffff0000, v216
	v_lshlrev_b32_e32 v162, 16, v217
	v_and_b32_e32 v163, 0xffff0000, v217
	v_lshlrev_b32_e32 v216, 16, v218
	v_and_b32_e32 v217, 0xffff0000, v218
	v_lshlrev_b32_e32 v218, 16, v219
	v_and_b32_e32 v219, 0xffff0000, v219
	v_pk_fma_f32 v[84:85], v[84:85], v[136:137], v[160:161]
	v_pk_fma_f32 v[86:87], v[86:87], v[138:139], v[162:163]
	v_pk_fma_f32 v[80:81], v[80:81], v[128:129], v[216:217]
	v_pk_fma_f32 v[82:83], v[82:83], v[130:131], v[218:219]
	v_cvt_pk_bf16_f32 v84, v84, v85
	v_cvt_pk_bf16_f32 v85, v86, v87
	v_cvt_pk_bf16_f32 v86, v80, v81
	v_cvt_pk_bf16_f32 v87, v82, v83
	s_add_u32 s64, s12, 0x20000
	s_addc_u32 s65, s13, 0
	global_store_dwordx4 v196, v[84:87], s[64:65] offset:256
	s_waitcnt vmcnt(15)
	v_lshlrev_b32_e32 v160, 16, v220
	v_and_b32_e32 v161, 0xffff0000, v220
	v_lshlrev_b32_e32 v162, 16, v221
	v_and_b32_e32 v163, 0xffff0000, v221
	v_lshlrev_b32_e32 v220, 16, v222
	v_and_b32_e32 v221, 0xffff0000, v222
	v_lshlrev_b32_e32 v222, 16, v223
	v_and_b32_e32 v223, 0xffff0000, v223
	v_pk_fma_f32 v[76:77], v[76:77], v[152:153], v[160:161]
	v_pk_fma_f32 v[78:79], v[78:79], v[154:155], v[162:163]
	v_pk_fma_f32 v[72:73], v[72:73], v[144:145], v[220:221]
	v_pk_fma_f32 v[74:75], v[74:75], v[146:147], v[222:223]
	v_cvt_pk_bf16_f32 v76, v76, v77
	v_cvt_pk_bf16_f32 v77, v78, v79
	v_cvt_pk_bf16_f32 v78, v72, v73
	v_cvt_pk_bf16_f32 v79, v74, v75
	s_add_u32 s64, s12, 0x30000
	s_addc_u32 s65, s13, 0
	global_store_dwordx4 v196, v[76:79], s[64:65]
	s_waitcnt vmcnt(15)
	v_lshlrev_b32_e32 v160, 16, v224
	v_and_b32_e32 v161, 0xffff0000, v224
	v_lshlrev_b32_e32 v162, 16, v225
	v_and_b32_e32 v163, 0xffff0000, v225
	v_lshlrev_b32_e32 v224, 16, v226
	v_and_b32_e32 v225, 0xffff0000, v226
	v_lshlrev_b32_e32 v226, 16, v227
	v_and_b32_e32 v227, 0xffff0000, v227
	v_pk_fma_f32 v[68:69], v[68:69], v[136:137], v[160:161]
	v_pk_fma_f32 v[70:71], v[70:71], v[138:139], v[162:163]
	v_pk_fma_f32 v[64:65], v[64:65], v[128:129], v[224:225]
	v_pk_fma_f32 v[66:67], v[66:67], v[130:131], v[226:227]
	v_cvt_pk_bf16_f32 v68, v68, v69
	v_cvt_pk_bf16_f32 v69, v70, v71
	v_cvt_pk_bf16_f32 v70, v64, v65
	v_cvt_pk_bf16_f32 v71, v66, v67
	s_add_u32 s64, s12, 0x30000
	s_addc_u32 s65, s13, 0
	global_store_dwordx4 v196, v[68:71], s[64:65] offset:256
	s_waitcnt vmcnt(15)
	v_lshlrev_b32_e32 v160, 16, v148
	v_and_b32_e32 v161, 0xffff0000, v148
	v_lshlrev_b32_e32 v162, 16, v149
	v_and_b32_e32 v163, 0xffff0000, v149
	v_lshlrev_b32_e32 v148, 16, v150
	v_and_b32_e32 v149, 0xffff0000, v150
	v_lshlrev_b32_e32 v150, 16, v151
	v_and_b32_e32 v151, 0xffff0000, v151
	v_pk_fma_f32 v[60:61], v[60:61], v[152:153], v[160:161]
	v_pk_fma_f32 v[62:63], v[62:63], v[154:155], v[162:163]
	v_pk_fma_f32 v[56:57], v[56:57], v[144:145], v[148:149]
	v_pk_fma_f32 v[58:59], v[58:59], v[146:147], v[150:151]
	v_cvt_pk_bf16_f32 v60, v60, v61
	v_cvt_pk_bf16_f32 v61, v62, v63
	v_cvt_pk_bf16_f32 v62, v56, v57
	v_cvt_pk_bf16_f32 v63, v58, v59
	s_add_u32 s64, s12, 0x80000
	s_addc_u32 s65, s13, 0
	global_store_dwordx4 v196, v[60:63], s[64:65]
	s_waitcnt vmcnt(15)
	v_lshlrev_b32_e32 v160, 16, v156
	v_and_b32_e32 v161, 0xffff0000, v156
	v_lshlrev_b32_e32 v162, 16, v157
	v_and_b32_e32 v163, 0xffff0000, v157
	v_lshlrev_b32_e32 v156, 16, v158
	v_and_b32_e32 v157, 0xffff0000, v158
	v_lshlrev_b32_e32 v158, 16, v159
	v_and_b32_e32 v159, 0xffff0000, v159
	v_pk_fma_f32 v[52:53], v[52:53], v[136:137], v[160:161]
	v_pk_fma_f32 v[54:55], v[54:55], v[138:139], v[162:163]
	v_pk_fma_f32 v[48:49], v[48:49], v[128:129], v[156:157]
	v_pk_fma_f32 v[50:51], v[50:51], v[130:131], v[158:159]
	v_cvt_pk_bf16_f32 v52, v52, v53
	v_cvt_pk_bf16_f32 v53, v54, v55
	v_cvt_pk_bf16_f32 v54, v48, v49
	v_cvt_pk_bf16_f32 v55, v50, v51
	s_add_u32 s64, s12, 0x80000
	s_addc_u32 s65, s13, 0
	global_store_dwordx4 v196, v[52:55], s[64:65] offset:256
	s_waitcnt vmcnt(15)
	v_lshlrev_b32_e32 v160, 16, v132
	v_and_b32_e32 v161, 0xffff0000, v132
	v_lshlrev_b32_e32 v162, 16, v133
	v_and_b32_e32 v163, 0xffff0000, v133
	v_lshlrev_b32_e32 v132, 16, v134
	v_and_b32_e32 v133, 0xffff0000, v134
	v_lshlrev_b32_e32 v134, 16, v135
	v_and_b32_e32 v135, 0xffff0000, v135
	v_pk_fma_f32 v[44:45], v[44:45], v[152:153], v[160:161]
	v_pk_fma_f32 v[46:47], v[46:47], v[154:155], v[162:163]
	v_pk_fma_f32 v[40:41], v[40:41], v[144:145], v[132:133]
	v_pk_fma_f32 v[42:43], v[42:43], v[146:147], v[134:135]
	v_cvt_pk_bf16_f32 v44, v44, v45
	v_cvt_pk_bf16_f32 v45, v46, v47
	v_cvt_pk_bf16_f32 v46, v40, v41
	v_cvt_pk_bf16_f32 v47, v42, v43
	s_add_u32 s64, s12, 0x90000
	s_addc_u32 s65, s13, 0
	global_store_dwordx4 v196, v[44:47], s[64:65]
	s_waitcnt vmcnt(15)
	v_lshlrev_b32_e32 v160, 16, v140
	v_and_b32_e32 v161, 0xffff0000, v140
	v_lshlrev_b32_e32 v162, 16, v141
	v_and_b32_e32 v163, 0xffff0000, v141
	v_lshlrev_b32_e32 v140, 16, v142
	v_and_b32_e32 v141, 0xffff0000, v142
	v_lshlrev_b32_e32 v142, 16, v143
	v_and_b32_e32 v143, 0xffff0000, v143
	v_pk_fma_f32 v[36:37], v[36:37], v[136:137], v[160:161]
	v_pk_fma_f32 v[38:39], v[38:39], v[138:139], v[162:163]
	v_pk_fma_f32 v[32:33], v[32:33], v[128:129], v[140:141]
	v_pk_fma_f32 v[34:35], v[34:35], v[130:131], v[142:143]
	v_cvt_pk_bf16_f32 v36, v36, v37
	v_cvt_pk_bf16_f32 v37, v38, v39
	v_cvt_pk_bf16_f32 v38, v32, v33
	v_cvt_pk_bf16_f32 v39, v34, v35
	s_add_u32 s64, s12, 0x90000
	s_addc_u32 s65, s13, 0
	global_store_dwordx4 v196, v[36:39], s[64:65] offset:256
	s_waitcnt vmcnt(15)
	v_lshlrev_b32_e32 v160, 16, v164
	v_and_b32_e32 v161, 0xffff0000, v164
	v_lshlrev_b32_e32 v162, 16, v165
	v_and_b32_e32 v163, 0xffff0000, v165
	v_lshlrev_b32_e32 v164, 16, v166
	v_and_b32_e32 v165, 0xffff0000, v166
	v_lshlrev_b32_e32 v166, 16, v167
	v_and_b32_e32 v167, 0xffff0000, v167
	v_pk_fma_f32 v[28:29], v[28:29], v[152:153], v[160:161]
	v_pk_fma_f32 v[30:31], v[30:31], v[154:155], v[162:163]
	v_pk_fma_f32 v[24:25], v[24:25], v[144:145], v[164:165]
	v_pk_fma_f32 v[26:27], v[26:27], v[146:147], v[166:167]
	v_cvt_pk_bf16_f32 v28, v28, v29
	v_cvt_pk_bf16_f32 v29, v30, v31
	v_cvt_pk_bf16_f32 v30, v24, v25
	v_cvt_pk_bf16_f32 v31, v26, v27
	s_add_u32 s64, s12, 0xa0000
	s_addc_u32 s65, s13, 0
	global_store_dwordx4 v196, v[28:31], s[64:65]
	s_waitcnt vmcnt(14)
	v_lshlrev_b32_e32 v160, 16, v184
	v_and_b32_e32 v161, 0xffff0000, v184
	v_lshlrev_b32_e32 v162, 16, v185
	v_and_b32_e32 v163, 0xffff0000, v185
	v_lshlrev_b32_e32 v184, 16, v186
	v_and_b32_e32 v185, 0xffff0000, v186
	v_lshlrev_b32_e32 v186, 16, v187
	v_and_b32_e32 v187, 0xffff0000, v187
	v_pk_fma_f32 v[20:21], v[20:21], v[136:137], v[160:161]
	v_pk_fma_f32 v[22:23], v[22:23], v[138:139], v[162:163]
	v_pk_fma_f32 v[16:17], v[16:17], v[128:129], v[184:185]
	v_pk_fma_f32 v[18:19], v[18:19], v[130:131], v[186:187]
	v_cvt_pk_bf16_f32 v20, v20, v21
	v_cvt_pk_bf16_f32 v21, v22, v23
	v_cvt_pk_bf16_f32 v22, v16, v17
	v_cvt_pk_bf16_f32 v23, v18, v19
	s_add_u32 s64, s12, 0xa0000
	s_addc_u32 s65, s13, 0
	global_store_dwordx4 v196, v[20:23], s[64:65] offset:256
	s_waitcnt vmcnt(13)
	v_lshlrev_b32_e32 v160, 16, v188
	v_and_b32_e32 v161, 0xffff0000, v188
	v_lshlrev_b32_e32 v162, 16, v189
	v_and_b32_e32 v163, 0xffff0000, v189
	v_lshlrev_b32_e32 v188, 16, v190
	v_and_b32_e32 v189, 0xffff0000, v190
	v_lshlrev_b32_e32 v190, 16, v191
	v_and_b32_e32 v191, 0xffff0000, v191
	v_pk_fma_f32 v[12:13], v[12:13], v[152:153], v[160:161]
	v_pk_fma_f32 v[14:15], v[14:15], v[154:155], v[162:163]
	v_pk_fma_f32 v[8:9], v[8:9], v[144:145], v[188:189]
	v_pk_fma_f32 v[10:11], v[10:11], v[146:147], v[190:191]
	v_cvt_pk_bf16_f32 v12, v12, v13
	v_cvt_pk_bf16_f32 v13, v14, v15
	v_cvt_pk_bf16_f32 v14, v8, v9
	v_cvt_pk_bf16_f32 v15, v10, v11
	s_add_u32 s64, s12, 0xb0000
	s_addc_u32 s65, s13, 0
	global_store_dwordx4 v196, v[12:15], s[64:65]
	s_waitcnt vmcnt(12)
	v_lshlrev_b32_e32 v160, 16, v208
	v_and_b32_e32 v161, 0xffff0000, v208
	v_lshlrev_b32_e32 v162, 16, v209
	v_and_b32_e32 v163, 0xffff0000, v209
	v_lshlrev_b32_e32 v208, 16, v210
	v_and_b32_e32 v209, 0xffff0000, v210
	v_lshlrev_b32_e32 v210, 16, v211
	v_and_b32_e32 v211, 0xffff0000, v211
	v_pk_fma_f32 v[4:5], v[4:5], v[136:137], v[160:161]
	v_pk_fma_f32 v[6:7], v[6:7], v[138:139], v[162:163]
	v_pk_fma_f32 v[0:1], v[0:1], v[128:129], v[208:209]
	v_pk_fma_f32 v[2:3], v[2:3], v[130:131], v[210:211]
	v_cvt_pk_bf16_f32 v4, v4, v5
	v_cvt_pk_bf16_f32 v5, v6, v7
	v_cvt_pk_bf16_f32 v6, v0, v1
	v_cvt_pk_bf16_f32 v7, v2, v3
	s_add_u32 s64, s12, 0xb0000
	s_addc_u32 s65, s13, 0
	global_store_dwordx4 v196, v[4:7], s[64:65] offset:256
	s_branch .Lres_done

.LBB0_639:
	s_add_i32 s60, s30, 2
	s_add_u32 s29, s26, 0x80
	s_addc_u32 s31, s27, 0
	s_add_i32 s34, 0, 0x10000
	v_add_u32_e32 v156, s34, v141
	ds_read_b128 v[144:147], v156
	ds_read_b128 v[148:151], v156 offset:1024
	ds_read_b128 v[152:155], v156 offset:2048
	ds_read_b128 v[156:159], v156 offset:3072
	s_cmp_eq_u32 s58, s30
	s_cselect_b32 s30, s20, s29
	s_cselect_b32 s31, s21, s31
	s_cselect_b32 s43, s25, s15
	s_cselect_b32 s42, s24, s13
	v_lshl_add_u64 v[196:197], s[26:27], 0, v[136:137]
	s_add_i32 m0, s17, 0xc000
	ds_read_b128 v[160:163], v143
	ds_read_b128 v[164:167], v143 offset:1024
	ds_read_b128 v[168:171], v143 offset:2048
	ds_read_b128 v[172:175], v143 offset:3072
	ds_read_b128 v[180:183], v143 offset:4096
	ds_read_b128 v[184:187], v143 offset:5120
	ds_read_b128 v[188:191], v143 offset:6144
	ds_read_b128 v[192:195], v143 offset:7168
	global_load_lds_dwordx4 v[196:197], off
	v_lshl_add_u64 v[196:197], s[26:27], 0, v[138:139]
	s_add_i32 m0, s17, 0xe000
	s_nop 0
	global_load_lds_dwordx4 v[196:197], off
	s_waitcnt lgkmcnt(8)
	s_barrier
	s_waitcnt lgkmcnt(0)
	v_mfma_f32_16x16x32_bf16 v[124:127], v[144:147], v[160:163], v[124:127]
	v_mfma_f32_16x16x32_bf16 v[120:123], v[152:155], v[160:163], v[120:123]
	v_mfma_f32_16x16x32_bf16 v[116:119], v[144:147], v[168:171], v[116:119]
	v_mfma_f32_16x16x32_bf16 v[112:115], v[152:155], v[168:171], v[112:115]
	v_mfma_f32_16x16x32_bf16 v[108:111], v[144:147], v[180:183], v[108:111]
	v_mfma_f32_16x16x32_bf16 v[104:107], v[152:155], v[180:183], v[104:107]
	v_mfma_f32_16x16x32_bf16 v[100:103], v[144:147], v[188:191], v[100:103]
	v_mfma_f32_16x16x32_bf16 v[96:99], v[152:155], v[188:191], v[96:99]
	v_mfma_f32_16x16x32_bf16 v[124:127], v[148:151], v[164:167], v[124:127]
	v_mfma_f32_16x16x32_bf16 v[120:123], v[156:159], v[164:167], v[120:123]
	v_mfma_f32_16x16x32_bf16 v[116:119], v[148:151], v[172:175], v[116:119]
	v_mfma_f32_16x16x32_bf16 v[112:115], v[156:159], v[172:175], v[112:115]
	v_mfma_f32_16x16x32_bf16 v[108:111], v[148:151], v[184:187], v[108:111]
	v_mfma_f32_16x16x32_bf16 v[104:107], v[156:159], v[184:187], v[104:107]
	v_mfma_f32_16x16x32_bf16 v[100:103], v[148:151], v[192:195], v[100:103]
	v_mfma_f32_16x16x32_bf16 v[96:99], v[156:159], v[192:195], v[96:99]
	s_barrier
	s_add_i32 s29, 0, 0x14000
	s_add_i32 s34, s34, s48
	v_add_u32_e32 v176, s29, v141
	v_lshl_add_u64 v[200:201], s[42:43], 0, v[130:131]
	s_mov_b32 m0, s34
	ds_read_b128 v[196:199], v176
	ds_read_b128 v[208:211], v176 offset:1024
	ds_read_b128 v[212:215], v176 offset:2048
	ds_read_b128 v[216:219], v176 offset:3072
	global_load_lds_dwordx4 v[200:201], off
	v_lshl_add_u64 v[220:221], s[42:43], 0, v[134:135]
	s_add_i32 m0, s34, 0x2000
	s_nop 0
	global_load_lds_dwordx4 v[220:221], off
	s_barrier
	s_waitcnt lgkmcnt(0)
	v_mfma_f32_16x16x32_bf16 v[72:75], v[196:199], v[160:163], v[72:75]
	v_mfma_f32_16x16x32_bf16 v[64:67], v[212:215], v[160:163], v[64:67]
	v_mfma_f32_16x16x32_bf16 v[56:59], v[196:199], v[168:171], v[56:59]
	v_mfma_f32_16x16x32_bf16 v[48:51], v[212:215], v[168:171], v[48:51]
	v_mfma_f32_16x16x32_bf16 v[44:47], v[196:199], v[180:183], v[44:47]
	v_mfma_f32_16x16x32_bf16 v[40:43], v[212:215], v[180:183], v[40:43]
	v_mfma_f32_16x16x32_bf16 v[36:39], v[196:199], v[188:191], v[36:39]
	v_mfma_f32_16x16x32_bf16 v[32:35], v[212:215], v[188:191], v[32:35]
	v_mfma_f32_16x16x32_bf16 v[72:75], v[208:211], v[164:167], v[72:75]
	v_mfma_f32_16x16x32_bf16 v[64:67], v[216:219], v[164:167], v[64:67]
	v_mfma_f32_16x16x32_bf16 v[56:59], v[208:211], v[172:175], v[56:59]
	v_mfma_f32_16x16x32_bf16 v[48:51], v[216:219], v[172:175], v[48:51]
	v_mfma_f32_16x16x32_bf16 v[44:47], v[208:211], v[184:187], v[44:47]
	v_mfma_f32_16x16x32_bf16 v[40:43], v[216:219], v[184:187], v[40:43]
	v_mfma_f32_16x16x32_bf16 v[36:39], v[208:211], v[192:195], v[36:39]
	v_mfma_f32_16x16x32_bf16 v[32:35], v[216:219], v[192:195], v[32:35]
	s_barrier
	s_mov_b32 m0, s17
	v_lshl_add_u64 v[222:223], s[30:31], 0, v[128:129]
	ds_read_b128 v[160:163], v143 offset:16384
	ds_read_b128 v[164:167], v143 offset:17408
	ds_read_b128 v[168:171], v143 offset:18432
	ds_read_b128 v[172:175], v143 offset:19456
	ds_read_b128 v[180:183], v143 offset:20480
	ds_read_b128 v[184:187], v143 offset:21504
	ds_read_b128 v[188:191], v143 offset:22528
	ds_read_b128 v[192:195], v143 offset:23552
	global_load_lds_dwordx4 v[222:223], off
	v_lshl_add_u64 v[224:225], s[30:31], 0, v[132:133]
	s_mov_b32 m0, s19
	s_nop 0
	global_load_lds_dwordx4 v[224:225], off
	s_barrier
	s_waitcnt lgkmcnt(0)
	v_mfma_f32_16x16x32_bf16 v[92:95], v[144:147], v[160:163], v[92:95]
	v_mfma_f32_16x16x32_bf16 v[88:91], v[152:155], v[160:163], v[88:91]
	v_mfma_f32_16x16x32_bf16 v[84:87], v[144:147], v[168:171], v[84:87]
	v_mfma_f32_16x16x32_bf16 v[80:83], v[152:155], v[168:171], v[80:83]
	v_mfma_f32_16x16x32_bf16 v[76:79], v[144:147], v[180:183], v[76:79]
	v_mfma_f32_16x16x32_bf16 v[68:71], v[152:155], v[180:183], v[68:71]
	v_mfma_f32_16x16x32_bf16 v[60:63], v[144:147], v[188:191], v[60:63]
	v_mfma_f32_16x16x32_bf16 v[52:55], v[152:155], v[188:191], v[52:55]
	v_mfma_f32_16x16x32_bf16 v[92:95], v[148:151], v[164:167], v[92:95]
	v_mfma_f32_16x16x32_bf16 v[88:91], v[156:159], v[164:167], v[88:91]
	v_mfma_f32_16x16x32_bf16 v[84:87], v[148:151], v[172:175], v[84:87]
	v_mfma_f32_16x16x32_bf16 v[80:83], v[156:159], v[172:175], v[80:83]
	v_mfma_f32_16x16x32_bf16 v[76:79], v[148:151], v[184:187], v[76:79]
	v_mfma_f32_16x16x32_bf16 v[68:71], v[156:159], v[184:187], v[68:71]
	v_mfma_f32_16x16x32_bf16 v[60:63], v[148:151], v[192:195], v[60:63]
	v_mfma_f32_16x16x32_bf16 v[52:55], v[156:159], v[192:195], v[52:55]
	s_barrier
	s_add_u32 s34, s42, s44
	s_addc_u32 s35, s43, 0
	s_add_i32 s29, s29, s48
	v_lshl_add_u64 v[226:227], s[34:35], 0, v[130:131]
	s_mov_b32 m0, s29
	v_lshl_add_u64 v[228:229], s[34:35], 0, v[134:135]
	global_load_lds_dwordx4 v[226:227], off
	s_add_i32 m0, s29, 0x2000
	s_nop 0
	global_load_lds_dwordx4 v[228:229], off
	s_waitcnt vmcnt(6)
	s_barrier
	v_mfma_f32_16x16x32_bf16 v[28:31], v[196:199], v[160:163], v[28:31]
	v_mfma_f32_16x16x32_bf16 v[24:27], v[212:215], v[160:163], v[24:27]
	v_mfma_f32_16x16x32_bf16 v[20:23], v[196:199], v[168:171], v[20:23]
	v_mfma_f32_16x16x32_bf16 v[16:19], v[212:215], v[168:171], v[16:19]
	v_mfma_f32_16x16x32_bf16 v[12:15], v[196:199], v[180:183], v[12:15]
	v_mfma_f32_16x16x32_bf16 v[8:11], v[212:215], v[180:183], v[8:11]
	v_mfma_f32_16x16x32_bf16 v[4:7], v[196:199], v[188:191], v[4:7]
	v_mfma_f32_16x16x32_bf16 v[0:3], v[212:215], v[188:191], v[0:3]
	v_mfma_f32_16x16x32_bf16 v[28:31], v[208:211], v[164:167], v[28:31]
	v_mfma_f32_16x16x32_bf16 v[24:27], v[216:219], v[164:167], v[24:27]
	v_mfma_f32_16x16x32_bf16 v[20:23], v[208:211], v[172:175], v[20:23]
	v_mfma_f32_16x16x32_bf16 v[16:19], v[216:219], v[172:175], v[16:19]
	v_mfma_f32_16x16x32_bf16 v[12:15], v[208:211], v[184:187], v[12:15]
	v_mfma_f32_16x16x32_bf16 v[8:11], v[216:219], v[184:187], v[8:11]
	v_mfma_f32_16x16x32_bf16 v[4:7], v[208:211], v[192:195], v[4:7]
	v_mfma_f32_16x16x32_bf16 v[0:3], v[216:219], v[192:195], v[0:3]
	s_barrier
	s_add_i32 s29, 0, 0x18000
	v_add_u32_e32 v156, s29, v141
	ds_read_b128 v[144:147], v156
	ds_read_b128 v[148:151], v156 offset:1024
	ds_read_b128 v[152:155], v156 offset:2048
	ds_read_b128 v[156:159], v156 offset:3072
	s_add_u32 s30, s30, s44
	s_addc_u32 s31, s31, 0
	s_mov_b32 m0, s51
	v_lshl_add_u64 v[196:197], s[30:31], 0, v[128:129]
	ds_read_b128 v[160:163], v143 offset:32768
	ds_read_b128 v[164:167], v143 offset:33792
	ds_read_b128 v[168:171], v143 offset:34816
	ds_read_b128 v[172:175], v143 offset:35840
	ds_read_b128 v[180:183], v143 offset:36864
	ds_read_b128 v[184:187], v143 offset:37888
	ds_read_b128 v[188:191], v143 offset:38912
	ds_read_b128 v[192:195], v143 offset:39936
	global_load_lds_dwordx4 v[196:197], off
	v_lshl_add_u64 v[196:197], s[30:31], 0, v[132:133]
	s_mov_b32 m0, s52
	s_nop 0
	global_load_lds_dwordx4 v[196:197], off
	s_waitcnt lgkmcnt(8)
	s_barrier
	s_waitcnt lgkmcnt(0)
	v_mfma_f32_16x16x32_bf16 v[124:127], v[144:147], v[160:163], v[124:127]
	v_mfma_f32_16x16x32_bf16 v[120:123], v[152:155], v[160:163], v[120:123]
	v_mfma_f32_16x16x32_bf16 v[116:119], v[144:147], v[168:171], v[116:119]
	v_mfma_f32_16x16x32_bf16 v[112:115], v[152:155], v[168:171], v[112:115]
	v_mfma_f32_16x16x32_bf16 v[108:111], v[144:147], v[180:183], v[108:111]
	v_mfma_f32_16x16x32_bf16 v[104:107], v[152:155], v[180:183], v[104:107]
	v_mfma_f32_16x16x32_bf16 v[100:103], v[144:147], v[188:191], v[100:103]
	v_mfma_f32_16x16x32_bf16 v[96:99], v[152:155], v[188:191], v[96:99]
	v_mfma_f32_16x16x32_bf16 v[124:127], v[148:151], v[164:167], v[124:127]
	v_mfma_f32_16x16x32_bf16 v[120:123], v[156:159], v[164:167], v[120:123]
	v_mfma_f32_16x16x32_bf16 v[116:119], v[148:151], v[172:175], v[116:119]
	v_mfma_f32_16x16x32_bf16 v[112:115], v[156:159], v[172:175], v[112:115]
	v_mfma_f32_16x16x32_bf16 v[108:111], v[148:151], v[184:187], v[108:111]
	v_mfma_f32_16x16x32_bf16 v[104:107], v[156:159], v[184:187], v[104:107]
	v_mfma_f32_16x16x32_bf16 v[100:103], v[148:151], v[192:195], v[100:103]
	v_mfma_f32_16x16x32_bf16 v[96:99], v[156:159], v[192:195], v[96:99]
	s_barrier
	s_add_i32 s30, 0, 0x1c000
	s_add_i32 s29, s29, s48
	v_add_u32_e32 v176, s30, v141
	v_lshl_add_u64 v[200:201], v[200:201], 0, s[40:41]
	s_mov_b32 m0, s29
	ds_read_b128 v[196:199], v176
	ds_read_b128 v[208:211], v176 offset:1024
	ds_read_b128 v[212:215], v176 offset:2048
	ds_read_b128 v[216:219], v176 offset:3072
	global_load_lds_dwordx4 v[200:201], off
	v_lshl_add_u64 v[200:201], v[220:221], 0, s[40:41]
	s_add_i32 m0, s29, 0x2000
	s_nop 0
	global_load_lds_dwordx4 v[200:201], off
	s_barrier
	s_waitcnt lgkmcnt(0)
	v_mfma_f32_16x16x32_bf16 v[72:75], v[196:199], v[160:163], v[72:75]
	v_mfma_f32_16x16x32_bf16 v[64:67], v[212:215], v[160:163], v[64:67]
	v_mfma_f32_16x16x32_bf16 v[56:59], v[196:199], v[168:171], v[56:59]
	v_mfma_f32_16x16x32_bf16 v[48:51], v[212:215], v[168:171], v[48:51]
	v_mfma_f32_16x16x32_bf16 v[44:47], v[196:199], v[180:183], v[44:47]
	v_mfma_f32_16x16x32_bf16 v[40:43], v[212:215], v[180:183], v[40:43]
	v_mfma_f32_16x16x32_bf16 v[36:39], v[196:199], v[188:191], v[36:39]
	v_mfma_f32_16x16x32_bf16 v[32:35], v[212:215], v[188:191], v[32:35]
	v_mfma_f32_16x16x32_bf16 v[72:75], v[208:211], v[164:167], v[72:75]
	v_mfma_f32_16x16x32_bf16 v[64:67], v[216:219], v[164:167], v[64:67]
	v_mfma_f32_16x16x32_bf16 v[56:59], v[208:211], v[172:175], v[56:59]
	v_mfma_f32_16x16x32_bf16 v[48:51], v[216:219], v[172:175], v[48:51]
	v_mfma_f32_16x16x32_bf16 v[44:47], v[208:211], v[184:187], v[44:47]
	v_mfma_f32_16x16x32_bf16 v[40:43], v[216:219], v[184:187], v[40:43]
	v_mfma_f32_16x16x32_bf16 v[36:39], v[208:211], v[192:195], v[36:39]
	v_mfma_f32_16x16x32_bf16 v[32:35], v[216:219], v[192:195], v[32:35]
	s_barrier
	s_mov_b32 m0, s56
	v_lshl_add_u64 v[200:201], v[222:223], 0, s[40:41]
	ds_read_b128 v[160:163], v143 offset:49152
	ds_read_b128 v[164:167], v143 offset:50176
	ds_read_b128 v[168:171], v143 offset:51200
	ds_read_b128 v[172:175], v143 offset:52224
	ds_read_b128 v[180:183], v143 offset:53248
	ds_read_b128 v[184:187], v143 offset:54272
	ds_read_b128 v[188:191], v143 offset:55296
	ds_read_b128 v[192:195], v143 offset:56320
	global_load_lds_dwordx4 v[200:201], off
	v_lshl_add_u64 v[200:201], v[224:225], 0, s[40:41]
	s_mov_b32 m0, s57
	s_nop 0
	global_load_lds_dwordx4 v[200:201], off
	s_barrier
	s_waitcnt lgkmcnt(0)
	v_mfma_f32_16x16x32_bf16 v[92:95], v[144:147], v[160:163], v[92:95]
	v_mfma_f32_16x16x32_bf16 v[88:91], v[152:155], v[160:163], v[88:91]
	v_mfma_f32_16x16x32_bf16 v[84:87], v[144:147], v[168:171], v[84:87]
	v_mfma_f32_16x16x32_bf16 v[80:83], v[152:155], v[168:171], v[80:83]
	v_mfma_f32_16x16x32_bf16 v[76:79], v[144:147], v[180:183], v[76:79]
	v_mfma_f32_16x16x32_bf16 v[68:71], v[152:155], v[180:183], v[68:71]
	v_mfma_f32_16x16x32_bf16 v[60:63], v[144:147], v[188:191], v[60:63]
	v_mfma_f32_16x16x32_bf16 v[52:55], v[152:155], v[188:191], v[52:55]
	v_mfma_f32_16x16x32_bf16 v[92:95], v[148:151], v[164:167], v[92:95]
	v_mfma_f32_16x16x32_bf16 v[88:91], v[156:159], v[164:167], v[88:91]
	v_mfma_f32_16x16x32_bf16 v[84:87], v[148:151], v[172:175], v[84:87]
	v_mfma_f32_16x16x32_bf16 v[80:83], v[156:159], v[172:175], v[80:83]
	v_mfma_f32_16x16x32_bf16 v[76:79], v[148:151], v[184:187], v[76:79]
	v_mfma_f32_16x16x32_bf16 v[68:71], v[156:159], v[184:187], v[68:71]
	v_mfma_f32_16x16x32_bf16 v[60:63], v[148:151], v[192:195], v[60:63]
	v_mfma_f32_16x16x32_bf16 v[52:55], v[156:159], v[192:195], v[52:55]
	s_barrier
	s_add_i32 s29, s30, s48
	v_lshl_add_u64 v[144:145], v[226:227], 0, s[40:41]
	s_mov_b32 m0, s29
	s_nop 0
	global_load_lds_dwordx4 v[144:145], off
	v_lshl_add_u64 v[144:145], v[228:229], 0, s[40:41]
	s_add_i32 m0, s29, 0x2000
	s_nop 0
	global_load_lds_dwordx4 v[144:145], off
	s_waitcnt vmcnt(6)
	s_barrier
	v_mfma_f32_16x16x32_bf16 v[28:31], v[196:199], v[160:163], v[28:31]
	v_mfma_f32_16x16x32_bf16 v[24:27], v[212:215], v[160:163], v[24:27]
	v_mfma_f32_16x16x32_bf16 v[20:23], v[196:199], v[168:171], v[20:23]
	v_mfma_f32_16x16x32_bf16 v[16:19], v[212:215], v[168:171], v[16:19]
	v_mfma_f32_16x16x32_bf16 v[12:15], v[196:199], v[180:183], v[12:15]
	v_mfma_f32_16x16x32_bf16 v[8:11], v[212:215], v[180:183], v[8:11]
	v_mfma_f32_16x16x32_bf16 v[4:7], v[196:199], v[188:191], v[4:7]
	v_mfma_f32_16x16x32_bf16 v[0:3], v[212:215], v[188:191], v[0:3]
	v_mfma_f32_16x16x32_bf16 v[28:31], v[208:211], v[164:167], v[28:31]
	v_mfma_f32_16x16x32_bf16 v[24:27], v[216:219], v[164:167], v[24:27]
	v_mfma_f32_16x16x32_bf16 v[20:23], v[208:211], v[172:175], v[20:23]
	v_mfma_f32_16x16x32_bf16 v[16:19], v[216:219], v[172:175], v[16:19]
	v_mfma_f32_16x16x32_bf16 v[12:15], v[208:211], v[184:187], v[12:15]
	v_mfma_f32_16x16x32_bf16 v[8:11], v[216:219], v[184:187], v[8:11]
	v_mfma_f32_16x16x32_bf16 v[4:7], v[208:211], v[192:195], v[4:7]
	v_mfma_f32_16x16x32_bf16 v[0:3], v[216:219], v[192:195], v[0:3]
	s_barrier
	s_add_u32 s26, s26, 0x100
	s_addc_u32 s27, s27, 0
	s_add_u32 s13, s13, 0x100
	s_addc_u32 s15, s15, 0
	s_cmp_ge_u32 s60, s55
	s_mov_b32 s30, s60
	s_cbranch_scc0 .LBB0_639
	s_lshl_b32 s13, s16, 8
	s_ashr_i32 s15, s16, 1
	s_and_b32 s13, s13, 0x100
	v_or_b32_e32 v145, s13, v142
	s_lshl_b32 s13, s15, s59
	s_add_i32 s26, s13, s54
	s_ashr_i32 s27, s26, 31
	s_lshl_b64 s[26:27], s[26:27], 12
	v_readlane_b32 s30, v255, 26
	v_lshl_add_u32 v144, s18, 8, v140
	v_readlane_b32 s31, v255, 27
	s_add_u32 s26, s30, s26
	s_addc_u32 s27, s31, s27
	v_lshlrev_b32_e32 v176, 1, v145
	v_pk_mul_f32 v[124:125], s[8:9], v[124:125]
	v_ashrrev_i32_e32 v145, 31, v144
	v_lshl_add_u64 v[146:147], s[26:27], 0, v[176:177]
	v_pk_mul_f32 v[148:149], s[10:11], v[122:123]
	v_pk_mul_f32 v[122:123], s[8:9], v[120:121]
	v_cvt_pk_bf16_f32 v120, v124, v125
	v_lshlrev_b64 v[124:125], 12, v[144:145]
	v_pk_mul_f32 v[126:127], s[10:11], v[126:127]
	v_lshl_add_u64 v[124:125], v[146:147], 0, v[124:125]
	v_cvt_pk_bf16_f32 v121, v126, v127
	v_pk_mul_f32 v[116:117], s[8:9], v[116:117]
	v_cvt_pk_bf16_f32 v122, v122, v123
	v_cvt_pk_bf16_f32 v123, v148, v149
	global_store_dwordx4 v[124:125], v[120:123], off offset:3072
	v_pk_mul_f32 v[118:119], s[10:11], v[118:119]
	v_pk_mul_f32 v[108:109], s[8:9], v[108:109]
	v_pk_mul_f32 v[120:121], s[10:11], v[114:115]
	v_pk_mul_f32 v[114:115], s[8:9], v[112:113]
	v_cvt_pk_bf16_f32 v112, v116, v117
	v_or_b32_e32 v116, 16, v144
	v_ashrrev_i32_e32 v117, 31, v116
	v_lshlrev_b64 v[116:117], 12, v[116:117]
	v_cvt_pk_bf16_f32 v113, v118, v119
	v_lshl_add_u64 v[116:117], v[146:147], 0, v[116:117]
	v_cvt_pk_bf16_f32 v114, v114, v115
	v_cvt_pk_bf16_f32 v115, v120, v121
	global_store_dwordx4 v[116:117], v[112:115], off offset:3072
	v_pk_mul_f32 v[110:111], s[10:11], v[110:111]
	v_pk_mul_f32 v[100:101], s[8:9], v[100:101]
	v_pk_mul_f32 v[112:113], s[10:11], v[106:107]
	v_pk_mul_f32 v[106:107], s[8:9], v[104:105]
	v_cvt_pk_bf16_f32 v104, v108, v109
	v_or_b32_e32 v108, 32, v144
	v_ashrrev_i32_e32 v109, 31, v108
	v_lshlrev_b64 v[108:109], 12, v[108:109]
	v_cvt_pk_bf16_f32 v105, v110, v111
	v_lshl_add_u64 v[108:109], v[146:147], 0, v[108:109]
	v_cvt_pk_bf16_f32 v106, v106, v107
	v_cvt_pk_bf16_f32 v107, v112, v113
	global_store_dwordx4 v[108:109], v[104:107], off offset:3072
	v_pk_mul_f32 v[102:103], s[10:11], v[102:103]
	v_pk_mul_f32 v[92:93], s[8:9], v[92:93]
	v_pk_mul_f32 v[104:105], s[10:11], v[98:99]
	v_pk_mul_f32 v[98:99], s[8:9], v[96:97]
	v_cvt_pk_bf16_f32 v96, v100, v101
	v_or_b32_e32 v100, 48, v144
	v_ashrrev_i32_e32 v101, 31, v100
	v_lshlrev_b64 v[100:101], 12, v[100:101]
	v_cvt_pk_bf16_f32 v97, v102, v103
	v_lshl_add_u64 v[100:101], v[146:147], 0, v[100:101]
	s_mov_b64 s[26:27], 0x80000
	v_cvt_pk_bf16_f32 v98, v98, v99
	v_cvt_pk_bf16_f32 v99, v104, v105
	global_store_dwordx4 v[100:101], v[96:99], off offset:3072
	v_pk_mul_f32 v[94:95], s[10:11], v[94:95]
	v_pk_mul_f32 v[84:85], s[8:9], v[84:85]
	v_pk_mul_f32 v[96:97], s[10:11], v[90:91]
	v_pk_mul_f32 v[90:91], s[8:9], v[88:89]
	v_cvt_pk_bf16_f32 v88, v92, v93
	v_cvt_pk_bf16_f32 v89, v94, v95
	v_lshl_add_u64 v[92:93], v[124:125], 0, s[26:27]
	s_mov_b64 s[26:27], 0x90000
	v_cvt_pk_bf16_f32 v90, v90, v91
	v_cvt_pk_bf16_f32 v91, v96, v97
	global_store_dwordx4 v[92:93], v[88:91], off offset:3072
	v_pk_mul_f32 v[86:87], s[10:11], v[86:87]
	v_pk_mul_f32 v[76:77], s[8:9], v[76:77]
	v_pk_mul_f32 v[88:89], s[10:11], v[82:83]
	v_pk_mul_f32 v[82:83], s[8:9], v[80:81]
	v_cvt_pk_bf16_f32 v80, v84, v85
	v_cvt_pk_bf16_f32 v81, v86, v87
	v_lshl_add_u64 v[84:85], v[124:125], 0, s[26:27]
	s_mov_b64 s[26:27], 0xa0000
	v_cvt_pk_bf16_f32 v82, v82, v83
	v_cvt_pk_bf16_f32 v83, v88, v89
	global_store_dwordx4 v[84:85], v[80:83], off offset:3072
	v_pk_mul_f32 v[78:79], s[10:11], v[78:79]
	v_pk_mul_f32 v[60:61], s[8:9], v[60:61]
	v_pk_mul_f32 v[80:81], s[10:11], v[70:71]
	v_pk_mul_f32 v[70:71], s[8:9], v[68:69]
	v_cvt_pk_bf16_f32 v68, v76, v77
	v_cvt_pk_bf16_f32 v69, v78, v79
	v_lshl_add_u64 v[76:77], v[124:125], 0, s[26:27]
	v_cvt_pk_bf16_f32 v70, v70, v71
	v_cvt_pk_bf16_f32 v71, v80, v81
	global_store_dwordx4 v[76:77], v[68:71], off offset:3072
	s_mov_b64 s[26:27], 0xb0000
	v_pk_mul_f32 v[62:63], s[10:11], v[62:63]
	v_pk_mul_f32 v[68:69], s[10:11], v[54:55]
	v_pk_mul_f32 v[54:55], s[8:9], v[52:53]
	v_cvt_pk_bf16_f32 v52, v60, v61
	v_cvt_pk_bf16_f32 v53, v62, v63
	v_lshl_add_u64 v[60:61], v[124:125], 0, s[26:27]
	v_cvt_pk_bf16_f32 v54, v54, v55
	v_cvt_pk_bf16_f32 v55, v68, v69
	global_store_dwordx4 v[60:61], v[52:55], off offset:3072
	v_pk_mul_f32 v[62:63], s[10:11], v[66:67]
	v_pk_mul_f32 v[64:65], s[8:9], v[64:65]
	v_pk_mul_f32 v[54:55], s[10:11], v[74:75]
	v_pk_mul_f32 v[52:53], s[8:9], v[72:73]
	v_pk_mul_f32 v[46:47], s[10:11], v[46:47]
	v_cvt_pk_bf16_f32 v52, v52, v53
	v_cvt_pk_bf16_f32 v53, v54, v55
	v_cvt_pk_bf16_f32 v54, v64, v65
	v_cvt_pk_bf16_f32 v55, v62, v63
	global_store_dwordx4 v[124:125], v[52:55], off offset:3328
	v_pk_mul_f32 v[44:45], s[8:9], v[44:45]
	v_pk_mul_f32 v[38:39], s[10:11], v[38:39]
	v_pk_mul_f32 v[52:53], s[10:11], v[58:59]
	v_pk_mul_f32 v[54:55], s[8:9], v[56:57]
	v_pk_mul_f32 v[56:57], s[10:11], v[50:51]
	v_pk_mul_f32 v[50:51], s[8:9], v[48:49]
	v_cvt_pk_bf16_f32 v48, v54, v55
	v_cvt_pk_bf16_f32 v49, v52, v53
	v_pk_mul_f32 v[36:37], s[8:9], v[36:37]
	v_cvt_pk_bf16_f32 v50, v50, v51
	v_cvt_pk_bf16_f32 v51, v56, v57
	global_store_dwordx4 v[116:117], v[48:51], off offset:3328
	v_pk_mul_f32 v[30:31], s[10:11], v[30:31]
	v_pk_mul_f32 v[28:29], s[8:9], v[28:29]
	v_pk_mul_f32 v[48:49], s[10:11], v[42:43]
	v_pk_mul_f32 v[42:43], s[8:9], v[40:41]
	v_cvt_pk_bf16_f32 v40, v44, v45
	v_cvt_pk_bf16_f32 v41, v46, v47
	v_pk_mul_f32 v[22:23], s[10:11], v[22:23]
	v_cvt_pk_bf16_f32 v42, v42, v43
	v_cvt_pk_bf16_f32 v43, v48, v49
	global_store_dwordx4 v[108:109], v[40:43], off offset:3328
	v_pk_mul_f32 v[20:21], s[8:9], v[20:21]
	v_pk_mul_f32 v[14:15], s[10:11], v[14:15]
	v_pk_mul_f32 v[40:41], s[10:11], v[34:35]
	v_pk_mul_f32 v[34:35], s[8:9], v[32:33]
	v_cvt_pk_bf16_f32 v32, v36, v37
	v_cvt_pk_bf16_f32 v33, v38, v39
	v_pk_mul_f32 v[12:13], s[8:9], v[12:13]
	v_cvt_pk_bf16_f32 v34, v34, v35
	v_cvt_pk_bf16_f32 v35, v40, v41
	global_store_dwordx4 v[100:101], v[32:35], off offset:3328
	s_and_b64 vcc, exec, s[6:7]
	s_mov_b32 s16, s12
	v_pk_mul_f32 v[32:33], s[10:11], v[26:27]
	v_pk_mul_f32 v[26:27], s[8:9], v[24:25]
	v_cvt_pk_bf16_f32 v24, v28, v29
	v_cvt_pk_bf16_f32 v25, v30, v31
	s_mov_b32 s18, s14
	v_cvt_pk_bf16_f32 v26, v26, v27
	v_cvt_pk_bf16_f32 v27, v32, v33
	global_store_dwordx4 v[92:93], v[24:27], off offset:3328
	s_mov_b64 s[30:31], s[24:25]
	s_mov_b64 s[26:27], s[20:21]
	v_pk_mul_f32 v[24:25], s[10:11], v[18:19]
	v_pk_mul_f32 v[18:19], s[8:9], v[16:17]
	v_cvt_pk_bf16_f32 v16, v20, v21
	v_cvt_pk_bf16_f32 v17, v22, v23
	v_pk_mul_f32 v[6:7], s[10:11], v[6:7]
	v_cvt_pk_bf16_f32 v18, v18, v19
	v_cvt_pk_bf16_f32 v19, v24, v25
	global_store_dwordx4 v[84:85], v[16:19], off offset:3328
	v_pk_mul_f32 v[4:5], s[8:9], v[4:5]
	s_nop 0
	v_pk_mul_f32 v[16:17], s[10:11], v[10:11]
	v_pk_mul_f32 v[10:11], s[8:9], v[8:9]
	v_cvt_pk_bf16_f32 v8, v12, v13
	v_cvt_pk_bf16_f32 v9, v14, v15
	s_nop 0
	v_cvt_pk_bf16_f32 v10, v10, v11
	v_cvt_pk_bf16_f32 v11, v16, v17
	global_store_dwordx4 v[76:77], v[8:11], off offset:3328
	s_nop 1
	v_pk_mul_f32 v[8:9], s[10:11], v[2:3]
	v_pk_mul_f32 v[2:3], s[8:9], v[0:1]
	v_cvt_pk_bf16_f32 v0, v4, v5
	v_cvt_pk_bf16_f32 v1, v6, v7
	s_nop 0
	v_cvt_pk_bf16_f32 v2, v2, v3
	v_cvt_pk_bf16_f32 v3, v8, v9
	global_store_dwordx4 v[60:61], v[0:3], off offset:3328
	s_cbranch_vccz .LBB0_636
	s_waitcnt vmcnt(0)
	s_setprio 0
	s_cmpk_gt_u32 s1, 0xff
	s_cbranch_scc1 .LBB0_626
	s_barrier
	s_branch .LBB0_626

.LBB0_656:
	s_add_u32 s20, s18, 0xfff80080
	s_addc_u32 s21, s19, -1
	s_add_i32 s34, 0, 0x10000
	v_add_u32_e32 v152, s34, v174
	ds_read_b128 v[140:143], v152
	ds_read_b128 v[144:147], v152 offset:1024
	ds_read_b128 v[148:151], v152 offset:2048
	ds_read_b128 v[152:155], v152 offset:3072
	s_cmp_eq_u32 s54, 28
	s_cselect_b32 s25, s9, s21
	s_cselect_b32 s24, s15, s20
	s_cselect_b32 s21, s5, s53
	s_cselect_b32 s20, s17, s44
	v_lshl_add_u64 v[180:181], s[18:19], 0, v[136:137]
	s_add_i32 m0, s30, 0xc000
	ds_read_b128 v[156:159], v189
	ds_read_b128 v[160:163], v189 offset:1024
	ds_read_b128 v[164:167], v189 offset:2048
	ds_read_b128 v[168:171], v189 offset:3072
	ds_read_b128 v[190:193], v189 offset:4096
	ds_read_b128 v[194:197], v189 offset:5120
	ds_read_b128 v[198:201], v189 offset:6144
	ds_read_b128 v[208:211], v189 offset:7168
	global_load_lds_dwordx4 v[180:181], off
	v_lshl_add_u64 v[180:181], s[18:19], 0, v[138:139]
	s_add_i32 m0, s30, 0xe000
	s_nop 0
	global_load_lds_dwordx4 v[180:181], off
	s_waitcnt lgkmcnt(8)
	s_barrier
	s_waitcnt lgkmcnt(0)
	v_mfma_f32_16x16x32_bf16 v[124:127], v[140:143], v[156:159], v[124:127]
	v_mfma_f32_16x16x32_bf16 v[120:123], v[148:151], v[156:159], v[120:123]
	v_mfma_f32_16x16x32_bf16 v[108:111], v[140:143], v[164:167], v[108:111]
	v_mfma_f32_16x16x32_bf16 v[104:107], v[148:151], v[164:167], v[104:107]
	v_mfma_f32_16x16x32_bf16 v[92:95], v[140:143], v[190:193], v[92:95]
	v_mfma_f32_16x16x32_bf16 v[88:91], v[148:151], v[190:193], v[88:91]
	v_mfma_f32_16x16x32_bf16 v[76:79], v[140:143], v[198:201], v[76:79]
	v_mfma_f32_16x16x32_bf16 v[72:75], v[148:151], v[198:201], v[72:75]
	v_mfma_f32_16x16x32_bf16 v[124:127], v[144:147], v[160:163], v[124:127]
	v_mfma_f32_16x16x32_bf16 v[120:123], v[152:155], v[160:163], v[120:123]
	v_mfma_f32_16x16x32_bf16 v[108:111], v[144:147], v[168:171], v[108:111]
	v_mfma_f32_16x16x32_bf16 v[104:107], v[152:155], v[168:171], v[104:107]
	v_mfma_f32_16x16x32_bf16 v[92:95], v[144:147], v[194:197], v[92:95]
	v_mfma_f32_16x16x32_bf16 v[88:91], v[152:155], v[194:197], v[88:91]
	v_mfma_f32_16x16x32_bf16 v[76:79], v[144:147], v[208:211], v[76:79]
	v_mfma_f32_16x16x32_bf16 v[72:75], v[152:155], v[208:211], v[72:75]
	s_barrier
	s_add_i32 s35, 0, 0x14000
	s_add_i32 s34, s34, s28
	v_add_u32_e32 v176, s35, v174
	v_lshl_add_u64 v[180:181], s[20:21], 0, v[130:131]
	s_mov_b32 m0, s34
	ds_read_b128 v[212:215], v176
	ds_read_b128 v[216:219], v176 offset:1024
	ds_read_b128 v[220:223], v176 offset:2048
	ds_read_b128 v[224:227], v176 offset:3072
	global_load_lds_dwordx4 v[180:181], off
	v_lshl_add_u64 v[228:229], s[20:21], 0, v[134:135]
	s_add_i32 m0, s34, 0x2000
	s_nop 0
	global_load_lds_dwordx4 v[228:229], off
	s_barrier
	s_waitcnt lgkmcnt(0)
	v_mfma_f32_16x16x32_bf16 v[116:119], v[212:215], v[156:159], v[116:119]
	v_mfma_f32_16x16x32_bf16 v[112:115], v[220:223], v[156:159], v[112:115]
	v_mfma_f32_16x16x32_bf16 v[100:103], v[212:215], v[164:167], v[100:103]
	v_mfma_f32_16x16x32_bf16 v[96:99], v[220:223], v[164:167], v[96:99]
	v_mfma_f32_16x16x32_bf16 v[84:87], v[212:215], v[190:193], v[84:87]
	v_mfma_f32_16x16x32_bf16 v[80:83], v[220:223], v[190:193], v[80:83]
	v_mfma_f32_16x16x32_bf16 v[68:71], v[212:215], v[198:201], v[68:71]
	v_mfma_f32_16x16x32_bf16 v[64:67], v[220:223], v[198:201], v[64:67]
	v_mfma_f32_16x16x32_bf16 v[116:119], v[216:219], v[160:163], v[116:119]
	v_mfma_f32_16x16x32_bf16 v[112:115], v[224:227], v[160:163], v[112:115]
	v_mfma_f32_16x16x32_bf16 v[100:103], v[216:219], v[168:171], v[100:103]
	v_mfma_f32_16x16x32_bf16 v[96:99], v[224:227], v[168:171], v[96:99]
	v_mfma_f32_16x16x32_bf16 v[84:87], v[216:219], v[194:197], v[84:87]
	v_mfma_f32_16x16x32_bf16 v[80:83], v[224:227], v[194:197], v[80:83]
	v_mfma_f32_16x16x32_bf16 v[68:71], v[216:219], v[208:211], v[68:71]
	v_mfma_f32_16x16x32_bf16 v[64:67], v[224:227], v[208:211], v[64:67]
	s_barrier
	s_mov_b32 m0, s30
	v_lshl_add_u64 v[230:231], s[24:25], 0, v[128:129]
	ds_read_b128 v[156:159], v189 offset:16384
	ds_read_b128 v[160:163], v189 offset:17408
	ds_read_b128 v[164:167], v189 offset:18432
	ds_read_b128 v[168:171], v189 offset:19456
	ds_read_b128 v[190:193], v189 offset:20480
	ds_read_b128 v[194:197], v189 offset:21504
	ds_read_b128 v[198:201], v189 offset:22528
	ds_read_b128 v[208:211], v189 offset:23552
	global_load_lds_dwordx4 v[230:231], off
	v_lshl_add_u64 v[232:233], s[24:25], 0, v[132:133]
	s_mov_b32 m0, s31
	s_nop 0
	global_load_lds_dwordx4 v[232:233], off
	s_barrier
	s_waitcnt lgkmcnt(0)
	v_mfma_f32_16x16x32_bf16 v[60:63], v[140:143], v[156:159], v[60:63]
	v_mfma_f32_16x16x32_bf16 v[56:59], v[148:151], v[156:159], v[56:59]
	v_mfma_f32_16x16x32_bf16 v[44:47], v[140:143], v[164:167], v[44:47]
	v_mfma_f32_16x16x32_bf16 v[40:43], v[148:151], v[164:167], v[40:43]
	v_mfma_f32_16x16x32_bf16 v[28:31], v[140:143], v[190:193], v[28:31]
	v_mfma_f32_16x16x32_bf16 v[24:27], v[148:151], v[190:193], v[24:27]
	v_mfma_f32_16x16x32_bf16 v[12:15], v[140:143], v[198:201], v[12:15]
	v_mfma_f32_16x16x32_bf16 v[8:11], v[148:151], v[198:201], v[8:11]
	v_mfma_f32_16x16x32_bf16 v[60:63], v[144:147], v[160:163], v[60:63]
	v_mfma_f32_16x16x32_bf16 v[56:59], v[152:155], v[160:163], v[56:59]
	v_mfma_f32_16x16x32_bf16 v[44:47], v[144:147], v[168:171], v[44:47]
	v_mfma_f32_16x16x32_bf16 v[40:43], v[152:155], v[168:171], v[40:43]
	v_mfma_f32_16x16x32_bf16 v[28:31], v[144:147], v[194:197], v[28:31]
	v_mfma_f32_16x16x32_bf16 v[24:27], v[152:155], v[194:197], v[24:27]
	v_mfma_f32_16x16x32_bf16 v[12:15], v[144:147], v[208:211], v[12:15]
	v_mfma_f32_16x16x32_bf16 v[8:11], v[152:155], v[208:211], v[8:11]
	s_barrier
	s_add_u32 s56, s20, 0x80000
	s_addc_u32 s57, s21, 0
	s_add_i32 s34, s35, s28
	v_lshl_add_u64 v[140:141], s[56:57], 0, v[130:131]
	s_mov_b32 m0, s34
	s_nop 0
	global_load_lds_dwordx4 v[140:141], off
	v_lshl_add_u64 v[140:141], s[56:57], 0, v[134:135]
	s_add_i32 m0, s34, 0x2000
	s_nop 0
	global_load_lds_dwordx4 v[140:141], off
	s_waitcnt vmcnt(6)
	s_barrier
	v_mfma_f32_16x16x32_bf16 v[52:55], v[212:215], v[156:159], v[52:55]
	v_mfma_f32_16x16x32_bf16 v[48:51], v[220:223], v[156:159], v[48:51]
	v_mfma_f32_16x16x32_bf16 v[36:39], v[212:215], v[164:167], v[36:39]
	v_mfma_f32_16x16x32_bf16 v[32:35], v[220:223], v[164:167], v[32:35]
	v_mfma_f32_16x16x32_bf16 v[20:23], v[212:215], v[190:193], v[20:23]
	v_mfma_f32_16x16x32_bf16 v[16:19], v[220:223], v[190:193], v[16:19]
	v_mfma_f32_16x16x32_bf16 v[4:7], v[212:215], v[198:201], v[4:7]
	v_mfma_f32_16x16x32_bf16 v[0:3], v[220:223], v[198:201], v[0:3]
	v_mfma_f32_16x16x32_bf16 v[52:55], v[216:219], v[160:163], v[52:55]
	v_mfma_f32_16x16x32_bf16 v[48:51], v[224:227], v[160:163], v[48:51]
	v_mfma_f32_16x16x32_bf16 v[36:39], v[216:219], v[168:171], v[36:39]
	v_mfma_f32_16x16x32_bf16 v[32:35], v[224:227], v[168:171], v[32:35]
	v_mfma_f32_16x16x32_bf16 v[20:23], v[216:219], v[194:197], v[20:23]
	v_mfma_f32_16x16x32_bf16 v[16:19], v[224:227], v[194:197], v[16:19]
	v_mfma_f32_16x16x32_bf16 v[4:7], v[216:219], v[208:211], v[4:7]
	v_mfma_f32_16x16x32_bf16 v[0:3], v[224:227], v[208:211], v[0:3]
	s_barrier
	s_add_i32 s34, 0, 0x18000
	v_add_u32_e32 v152, s34, v174
	ds_read_b128 v[140:143], v152
	ds_read_b128 v[144:147], v152 offset:1024
	ds_read_b128 v[148:151], v152 offset:2048
	ds_read_b128 v[152:155], v152 offset:3072
	s_add_u32 s24, s24, 0x80000
	s_addc_u32 s25, s25, 0
	s_mov_b32 m0, s33
	v_lshl_add_u64 v[212:213], s[24:25], 0, v[128:129]
	ds_read_b128 v[156:159], v189 offset:32768
	ds_read_b128 v[160:163], v189 offset:33792
	ds_read_b128 v[164:167], v189 offset:34816
	ds_read_b128 v[168:171], v189 offset:35840
	ds_read_b128 v[190:193], v189 offset:36864
	ds_read_b128 v[194:197], v189 offset:37888
	ds_read_b128 v[198:201], v189 offset:38912
	ds_read_b128 v[208:211], v189 offset:39936
	global_load_lds_dwordx4 v[212:213], off
	v_lshl_add_u64 v[212:213], s[24:25], 0, v[132:133]
	s_mov_b32 m0, s37
	s_nop 0
	global_load_lds_dwordx4 v[212:213], off
	s_waitcnt lgkmcnt(8)
	s_barrier
	s_waitcnt lgkmcnt(0)
	v_mfma_f32_16x16x32_bf16 v[124:127], v[140:143], v[156:159], v[124:127]
	v_mfma_f32_16x16x32_bf16 v[120:123], v[148:151], v[156:159], v[120:123]
	v_mfma_f32_16x16x32_bf16 v[108:111], v[140:143], v[164:167], v[108:111]
	v_mfma_f32_16x16x32_bf16 v[104:107], v[148:151], v[164:167], v[104:107]
	v_mfma_f32_16x16x32_bf16 v[92:95], v[140:143], v[190:193], v[92:95]
	v_mfma_f32_16x16x32_bf16 v[88:91], v[148:151], v[190:193], v[88:91]
	v_mfma_f32_16x16x32_bf16 v[76:79], v[140:143], v[198:201], v[76:79]
	v_mfma_f32_16x16x32_bf16 v[72:75], v[148:151], v[198:201], v[72:75]
	v_mfma_f32_16x16x32_bf16 v[124:127], v[144:147], v[160:163], v[124:127]
	v_mfma_f32_16x16x32_bf16 v[120:123], v[152:155], v[160:163], v[120:123]
	v_mfma_f32_16x16x32_bf16 v[108:111], v[144:147], v[168:171], v[108:111]
	v_mfma_f32_16x16x32_bf16 v[104:107], v[152:155], v[168:171], v[104:107]
	v_mfma_f32_16x16x32_bf16 v[92:95], v[144:147], v[194:197], v[92:95]
	v_mfma_f32_16x16x32_bf16 v[88:91], v[152:155], v[194:197], v[88:91]
	v_mfma_f32_16x16x32_bf16 v[76:79], v[144:147], v[208:211], v[76:79]
	v_mfma_f32_16x16x32_bf16 v[72:75], v[152:155], v[208:211], v[72:75]
	s_barrier
	s_add_i32 s24, 0, 0x1c000
	s_add_i32 s25, s34, s28
	v_add_u32_e32 v176, s24, v174
	v_lshl_add_u64 v[180:181], v[180:181], 0, s[40:41]
	s_mov_b32 m0, s25
	ds_read_b128 v[212:215], v176
	ds_read_b128 v[216:219], v176 offset:1024
	ds_read_b128 v[220:223], v176 offset:2048
	ds_read_b128 v[224:227], v176 offset:3072
	global_load_lds_dwordx4 v[180:181], off
	v_lshl_add_u64 v[180:181], v[228:229], 0, s[40:41]
	s_add_i32 m0, s25, 0x2000
	s_nop 0
	global_load_lds_dwordx4 v[180:181], off
	s_barrier
	s_waitcnt lgkmcnt(0)
	v_mfma_f32_16x16x32_bf16 v[116:119], v[212:215], v[156:159], v[116:119]
	v_mfma_f32_16x16x32_bf16 v[112:115], v[220:223], v[156:159], v[112:115]
	v_mfma_f32_16x16x32_bf16 v[100:103], v[212:215], v[164:167], v[100:103]
	v_mfma_f32_16x16x32_bf16 v[96:99], v[220:223], v[164:167], v[96:99]
	v_mfma_f32_16x16x32_bf16 v[84:87], v[212:215], v[190:193], v[84:87]
	v_mfma_f32_16x16x32_bf16 v[80:83], v[220:223], v[190:193], v[80:83]
	v_mfma_f32_16x16x32_bf16 v[68:71], v[212:215], v[198:201], v[68:71]
	v_mfma_f32_16x16x32_bf16 v[64:67], v[220:223], v[198:201], v[64:67]
	v_mfma_f32_16x16x32_bf16 v[116:119], v[216:219], v[160:163], v[116:119]
	v_mfma_f32_16x16x32_bf16 v[112:115], v[224:227], v[160:163], v[112:115]
	v_mfma_f32_16x16x32_bf16 v[100:103], v[216:219], v[168:171], v[100:103]
	v_mfma_f32_16x16x32_bf16 v[96:99], v[224:227], v[168:171], v[96:99]
	v_mfma_f32_16x16x32_bf16 v[84:87], v[216:219], v[194:197], v[84:87]
	v_mfma_f32_16x16x32_bf16 v[80:83], v[224:227], v[194:197], v[80:83]
	v_mfma_f32_16x16x32_bf16 v[68:71], v[216:219], v[208:211], v[68:71]
	v_mfma_f32_16x16x32_bf16 v[64:67], v[224:227], v[208:211], v[64:67]
	s_barrier
	s_mov_b32 m0, s47
	v_lshl_add_u64 v[180:181], v[230:231], 0, s[40:41]
	ds_read_b128 v[156:159], v189 offset:49152
	ds_read_b128 v[160:163], v189 offset:50176
	ds_read_b128 v[164:167], v189 offset:51200
	ds_read_b128 v[168:171], v189 offset:52224
	ds_read_b128 v[190:193], v189 offset:53248
	ds_read_b128 v[194:197], v189 offset:54272
	ds_read_b128 v[198:201], v189 offset:55296
	ds_read_b128 v[208:211], v189 offset:56320
	global_load_lds_dwordx4 v[180:181], off
	v_lshl_add_u64 v[180:181], v[232:233], 0, s[40:41]
	s_mov_b32 m0, s48
	s_nop 0
	global_load_lds_dwordx4 v[180:181], off
	s_barrier
	s_waitcnt lgkmcnt(0)
	v_mfma_f32_16x16x32_bf16 v[60:63], v[140:143], v[156:159], v[60:63]
	v_mfma_f32_16x16x32_bf16 v[56:59], v[148:151], v[156:159], v[56:59]
	v_mfma_f32_16x16x32_bf16 v[44:47], v[140:143], v[164:167], v[44:47]
	v_mfma_f32_16x16x32_bf16 v[40:43], v[148:151], v[164:167], v[40:43]
	v_mfma_f32_16x16x32_bf16 v[28:31], v[140:143], v[190:193], v[28:31]
	v_mfma_f32_16x16x32_bf16 v[24:27], v[148:151], v[190:193], v[24:27]
	v_mfma_f32_16x16x32_bf16 v[12:15], v[140:143], v[198:201], v[12:15]
	v_mfma_f32_16x16x32_bf16 v[8:11], v[148:151], v[198:201], v[8:11]
	v_mfma_f32_16x16x32_bf16 v[60:63], v[144:147], v[160:163], v[60:63]
	v_mfma_f32_16x16x32_bf16 v[56:59], v[152:155], v[160:163], v[56:59]
	v_mfma_f32_16x16x32_bf16 v[44:47], v[144:147], v[168:171], v[44:47]
	v_mfma_f32_16x16x32_bf16 v[40:43], v[152:155], v[168:171], v[40:43]
	v_mfma_f32_16x16x32_bf16 v[28:31], v[144:147], v[194:197], v[28:31]
	v_mfma_f32_16x16x32_bf16 v[24:27], v[152:155], v[194:197], v[24:27]
	v_mfma_f32_16x16x32_bf16 v[12:15], v[144:147], v[208:211], v[12:15]
	v_mfma_f32_16x16x32_bf16 v[8:11], v[152:155], v[208:211], v[8:11]
	s_barrier
	s_add_u32 s20, s20, 0x80080
	s_addc_u32 s21, s21, 0
	s_add_i32 s24, s24, s28
	v_lshl_add_u64 v[140:141], s[20:21], 0, v[130:131]
	s_mov_b32 m0, s24
	s_nop 0
	global_load_lds_dwordx4 v[140:141], off
	v_lshl_add_u64 v[140:141], s[20:21], 0, v[134:135]
	s_add_i32 m0, s24, 0x2000
	s_nop 0
	global_load_lds_dwordx4 v[140:141], off
	s_waitcnt vmcnt(6)
	s_barrier
	v_mfma_f32_16x16x32_bf16 v[52:55], v[212:215], v[156:159], v[52:55]
	v_mfma_f32_16x16x32_bf16 v[48:51], v[220:223], v[156:159], v[48:51]
	v_mfma_f32_16x16x32_bf16 v[36:39], v[212:215], v[164:167], v[36:39]
	v_mfma_f32_16x16x32_bf16 v[32:35], v[220:223], v[164:167], v[32:35]
	v_mfma_f32_16x16x32_bf16 v[20:23], v[212:215], v[190:193], v[20:23]
	v_mfma_f32_16x16x32_bf16 v[16:19], v[220:223], v[190:193], v[16:19]
	v_mfma_f32_16x16x32_bf16 v[4:7], v[212:215], v[198:201], v[4:7]
	v_mfma_f32_16x16x32_bf16 v[0:3], v[220:223], v[198:201], v[0:3]
	v_mfma_f32_16x16x32_bf16 v[52:55], v[216:219], v[160:163], v[52:55]
	v_mfma_f32_16x16x32_bf16 v[48:51], v[224:227], v[160:163], v[48:51]
	v_mfma_f32_16x16x32_bf16 v[36:39], v[216:219], v[168:171], v[36:39]
	v_mfma_f32_16x16x32_bf16 v[32:35], v[224:227], v[168:171], v[32:35]
	v_mfma_f32_16x16x32_bf16 v[20:23], v[216:219], v[194:197], v[20:23]
	v_mfma_f32_16x16x32_bf16 v[16:19], v[224:227], v[194:197], v[16:19]
	v_mfma_f32_16x16x32_bf16 v[4:7], v[216:219], v[208:211], v[4:7]
	v_mfma_f32_16x16x32_bf16 v[0:3], v[224:227], v[208:211], v[0:3]
	s_barrier
	s_add_i32 s54, s54, 2
	s_add_u32 s44, s44, 0x100
	s_addc_u32 s53, s53, 0
	s_add_u32 s18, s18, 0x100
	s_addc_u32 s19, s19, 0
	s_cmp_gt_u32 s54, 29
	s_cbranch_scc0 .LBB0_656
	s_lshl_b32 s5, s16, 8
	s_cmp_lt_i32 s14, 18
	v_readlane_b32 s20, v255, 32
	s_cselect_b64 s[18:19], -1, 0
	v_readlane_b32 s21, v255, 33
	s_or_b64 s[20:21], s[20:21], s[18:19]
	s_mov_b64 s[18:19], -1
	s_and_b64 vcc, exec, s[20:21]
	v_mov_b32_e32 v198, 0xbf1f24be
	s_cbranch_vccnz .LBB0_664
	s_sub_i32 s9, s14, 18
	s_cmp_gt_i32 s16, 31
	s_cbranch_scc0 .LBB0_660
	s_sub_i32 s15, s16, 32
	s_lshr_b32 s15, s15, 1
	s_and_b32 s15, s15, 0x1fffffc
	s_add_i32 s15, s15, s9
	s_lshl_b32 s44, s15, 7
	s_lshl_b64 s[18:19], s[44:45], 13
	s_add_u32 s24, s38, s18
	s_addc_u32 s25, s39, s19
	s_and_b32 s15, s5, 0x700
	s_add_i32 s15, s15, s46
	s_mov_b64 s[18:19], 0
